# adds one barrier per load/MFMA segment pair in the K-loops (waves 0-3 sync after their load segment, waves 4-7 after their MFMA segment), no stagger/align barriers
# baseline (speedup 1.0000x reference)
_Z3fwd4Args:
	s_load_dwordx8 s[84:91], s[0:1], 0x80
	s_load_dword s14, s[0:1], 0xa8
	s_add_u32 s4, s0, 0xa8
	s_addc_u32 s5, s1, 0
	v_and_b32_e32 v66, 0x3ff, v0
	v_writelane_b32 v250, s4, 0
	s_waitcnt lgkmcnt(0)
	s_and_b32 s3, s14, 7
	v_readfirstlane_b32 s52, v66
	v_writelane_b32 v250, s5, 1
	s_lshr_b32 s101, s52, 8
	s_mov_b32 s4, s2
	v_writelane_b32 v250, s4, 2
	s_cmp_lg_u32 s3, 0
	s_nop 0
	v_writelane_b32 v250, s5, 3
	v_writelane_b32 v250, s2, 4
	s_cbranch_scc0 .LBB0_66
	s_movk_i32 s2, 0x100
	v_cmp_gt_u32_e64 s[6:7], s2, v66
	s_and_saveexec_b64 s[2:3], s[6:7]

.LBB0_133:
	s_mov_b32 s75, s35
	v_writelane_b32 v254, s74, 21
	v_and_b32_e32 v241, 63, v240
	s_andn2_b64 vcc, exec, s[0:1]
	v_writelane_b32 v254, s75, 22
	s_cbranch_vccnz .LBB0_449
	v_mov_b32_e32 v0, v81
	v_readlane_b32 s0, v251, 7
	v_mbcnt_lo_u32_b32 v0, -1, v0
	v_mbcnt_hi_u32_b32 v0, -1, v0
	v_add_u32_e32 v0, s69, v0
	v_readlane_b32 s1, v251, 8
	s_andn2_b64 vcc, exec, s[0:1]
	v_readfirstlane_b32 s0, v0
	s_cbranch_vccnz .LBB0_370
	s_ashr_i32 s4, s0, 6
	s_lshl_b32 s2, s4, 10
	v_readlane_b32 s6, v254, 19
	v_readlane_b32 s7, v254, 20
	s_add_i32 s31, s2, 0x100
	v_lshlrev_b32_e32 v242, 4, v0
	s_and_b32 s57, s7, 0xffff
	s_mov_b32 s56, s6
	s_add_i32 s51, s31, 0x10000
	v_readlane_b32 s2, v253, 29
	s_mov_b32 m0, s51
	s_nop 0
	buffer_load_dwordx4 v242, s[56:59], s2 offen lds
	v_add_u32_e32 v243, 0x2000, v242
	s_add_i32 s52, s31, 0x12000
	s_mov_b32 m0, s52
	s_nop 0
	buffer_load_dwordx4 v243, s[56:59], s2 offen lds
	s_add_i32 s53, s31, 0x14000
	v_readlane_b32 s2, v253, 23
	s_mov_b32 m0, s53
	s_nop 0
	buffer_load_dwordx4 v242, s[56:59], s2 offen lds
	s_add_i32 s55, s31, 0x16000
	s_mov_b32 m0, s55
	s_nop 0
	buffer_load_dwordx4 v243, s[56:59], s2 offen lds
	v_readlane_b32 s2, v253, 27
	s_mov_b32 m0, s31
	s_nop 0
	buffer_load_dwordx4 v242, s[24:27], s2 offen lds
	s_ashr_i32 s1, s0, 8
	s_add_i32 s68, s31, 0x2000
	s_mov_b32 m0, s68
	s_nop 0
	buffer_load_dwordx4 v243, s[24:27], s2 offen lds
	s_add_i32 s69, s31, 0x4000
	s_add_i32 s70, s31, 0x6000
	v_readlane_b32 s5, v253, 25
	s_mov_b32 m0, s69
	s_nop 0
	buffer_load_dwordx4 v242, s[24:27], s5 offen lds
	s_cmp_eq_u32 s1, 1
	s_cselect_b64 s[2:3], -1, 0
	s_mov_b32 m0, s70
	s_nop 0
	buffer_load_dwordx4 v243, s[24:27], s5 offen lds
	v_readlane_b32 s32, v253, 26
	v_readlane_b32 s98, v253, 28
	v_readlane_b32 s99, v253, 30
	s_nop 2
	s_add_i32 m0, s31, 0x18000
	s_nop 0
	buffer_load_dwordx4 v242, s[56:59], s32 offen lds
	s_add_i32 m0, s31, 0x1a000
	s_nop 0
	buffer_load_dwordx4 v243, s[56:59], s32 offen lds
	s_add_i32 m0, s31, 0x8000
	s_nop 0
	buffer_load_dwordx4 v242, s[24:27], s98 offen lds
	s_add_i32 m0, s31, 0xa000
	s_nop 0
	buffer_load_dwordx4 v243, s[24:27], s98 offen lds
	s_add_i32 m0, s31, 0x1c000
	s_nop 0
	buffer_load_dwordx4 v242, s[56:59], s99 offen lds
	s_add_i32 m0, s31, 0x1e000
	s_nop 0
	buffer_load_dwordx4 v243, s[56:59], s99 offen lds
	v_writelane_b32 v254, s2, 23
	s_movk_i32 s28, 0x3c0
	s_cmp_lg_u32 s1, 1
	v_writelane_b32 v254, s3, 24
	s_cbranch_scc1 .LBB0_137
	s_nop 0

.Lpeel_p1:
	s_waitcnt lgkmcnt(0)
	v_add_u32_e32 v28, 0x10000, v83
	v_add_u32_e32 v80, 0x14000, v83
	ds_read_b128 v[16:19], v28
	ds_read_b128 v[20:23], v28 offset:1024
	ds_read_b128 v[24:27], v28 offset:2048
	ds_read_b128 v[28:31], v28 offset:3072
	ds_read_b128 v[152:155], v80
	ds_read_b128 v[160:163], v80 offset:1024
	ds_read_b128 v[168:171], v80 offset:2048
	ds_read_b128 v[176:179], v80 offset:3072
	s_add_i32 s7, s4, 0xfff84000
	s_cmp_eq_u32 s6, 28
	s_cselect_b32 s17, s0, s7
	s_cselect_b32 s16, s1, s5
	s_or_b32 s7, s17, 0x4000
	ds_read_b128 v[192:195], v245
	ds_read_b128 v[196:199], v245 offset:1024
	ds_read_b128 v[200:203], v245 offset:2048
	ds_read_b128 v[204:207], v245 offset:3072
	ds_read_b128 v[220:223], v245 offset:4096
	ds_read_b128 v[224:227], v245 offset:5120
	ds_read_b128 v[228:231], v245 offset:6144
	ds_read_b128 v[246:249], v245 offset:7168
	s_mov_b32 m0, s79
	s_nop 0
	buffer_load_dwordx4 v242, s[24:27], s4 offen lds
	s_nop 0
	s_mov_b32 m0, s83
	s_nop 0
	buffer_load_dwordx4 v243, s[24:27], s4 offen lds
	s_waitcnt vmcnt(24)
	s_waitcnt lgkmcnt(0)
	s_cmp_lg_u32 s101, 0
	s_cbranch_scc1 .Lhbp_p1_0
	s_barrier
.Lhbp_p1_0:
	s_setprio 1
	s_waitcnt lgkmcnt(7)
	v_mfma_f32_16x16x32_bf16 v[180:183], v[16:19], v[192:195], 0
	v_mfma_f32_16x16x32_bf16 v[164:167], v[24:27], v[192:195], 0
	s_waitcnt lgkmcnt(5)
	v_mfma_f32_16x16x32_bf16 v[148:151], v[16:19], v[200:203], 0
	v_mfma_f32_16x16x32_bf16 v[140:143], v[24:27], v[200:203], 0
	s_waitcnt lgkmcnt(3)
	v_mfma_f32_16x16x32_bf16 v[132:135], v[16:19], v[220:223], 0
	v_mfma_f32_16x16x32_bf16 v[124:127], v[24:27], v[220:223], 0
	s_waitcnt lgkmcnt(1)
	v_mfma_f32_16x16x32_bf16 v[116:119], v[16:19], v[228:231], 0
	v_mfma_f32_16x16x32_bf16 v[108:111], v[24:27], v[228:231], 0
	v_mfma_f32_16x16x32_bf16 v[180:183], v[20:23], v[196:199], v[180:183]
	v_mfma_f32_16x16x32_bf16 v[164:167], v[28:31], v[196:199], v[164:167]
	v_mfma_f32_16x16x32_bf16 v[148:151], v[20:23], v[204:207], v[148:151]
	v_mfma_f32_16x16x32_bf16 v[140:143], v[28:31], v[204:207], v[140:143]
	v_mfma_f32_16x16x32_bf16 v[132:135], v[20:23], v[224:227], v[132:135]
	v_mfma_f32_16x16x32_bf16 v[124:127], v[28:31], v[224:227], v[124:127]
	s_waitcnt lgkmcnt(0)
	v_mfma_f32_16x16x32_bf16 v[116:119], v[20:23], v[246:249], v[116:119]
	v_mfma_f32_16x16x32_bf16 v[108:111], v[28:31], v[246:249], v[108:111]
	s_setprio 0
	s_setprio 1
	v_mfma_f32_16x16x32_bf16 v[172:175], v[152:155], v[192:195], 0
	v_mfma_f32_16x16x32_bf16 v[156:159], v[168:171], v[192:195], 0
	v_mfma_f32_16x16x32_bf16 v[144:147], v[152:155], v[200:203], 0
	v_mfma_f32_16x16x32_bf16 v[136:139], v[168:171], v[200:203], 0
	v_mfma_f32_16x16x32_bf16 v[128:131], v[152:155], v[220:223], 0
	v_mfma_f32_16x16x32_bf16 v[120:123], v[168:171], v[220:223], 0
	v_mfma_f32_16x16x32_bf16 v[112:115], v[152:155], v[228:231], 0
	v_mfma_f32_16x16x32_bf16 v[104:107], v[168:171], v[228:231], 0
	v_mfma_f32_16x16x32_bf16 v[172:175], v[160:163], v[196:199], v[172:175]
	v_mfma_f32_16x16x32_bf16 v[156:159], v[176:179], v[196:199], v[156:159]
	v_mfma_f32_16x16x32_bf16 v[144:147], v[160:163], v[204:207], v[144:147]
	v_mfma_f32_16x16x32_bf16 v[136:139], v[176:179], v[204:207], v[136:139]
	v_mfma_f32_16x16x32_bf16 v[128:131], v[160:163], v[224:227], v[128:131]
	v_mfma_f32_16x16x32_bf16 v[120:123], v[176:179], v[224:227], v[120:123]
	v_mfma_f32_16x16x32_bf16 v[112:115], v[160:163], v[246:249], v[112:115]
	v_mfma_f32_16x16x32_bf16 v[104:107], v[176:179], v[246:249], v[104:107]
	s_setprio 0
	s_cmp_eq_u32 s101, 0
	s_cbranch_scc1 .Lhbp_p1_1
	s_barrier
.Lhbp_p1_1:
	ds_read_b128 v[192:195], v245 offset:16384
	ds_read_b128 v[196:199], v245 offset:17408
	ds_read_b128 v[200:203], v245 offset:18432
	ds_read_b128 v[204:207], v245 offset:19456
	ds_read_b128 v[220:223], v245 offset:20480
	ds_read_b128 v[224:227], v245 offset:21504
	ds_read_b128 v[228:231], v245 offset:22528
	ds_read_b128 v[246:249], v245 offset:23552
	s_mov_b32 m0, s51
	s_nop 0
	buffer_load_dwordx4 v242, s[56:59], s16 offen lds
	s_add_i32 s18, s16, 0x80000
	s_mov_b32 m0, s52
	s_nop 0
	buffer_load_dwordx4 v243, s[56:59], s16 offen lds
	s_nop 0
	s_mov_b32 m0, s53
	s_nop 0
	buffer_load_dwordx4 v242, s[56:59], s18 offen lds
	s_nop 0
	s_mov_b32 m0, s55
	s_nop 0
	buffer_load_dwordx4 v243, s[56:59], s18 offen lds
	s_nop 0
	s_mov_b32 m0, s31
	s_nop 0
	buffer_load_dwordx4 v242, s[24:27], s17 offen lds
	s_nop 0
	s_mov_b32 m0, s68
	s_nop 0
	buffer_load_dwordx4 v243, s[24:27], s17 offen lds
	s_waitcnt vmcnt(24)
	s_waitcnt lgkmcnt(0)
	s_cmp_lg_u32 s101, 0
	s_cbranch_scc1 .Lhbp_p1_2
	s_barrier
.Lhbp_p1_2:
	s_setprio 1
	s_waitcnt lgkmcnt(7)
	v_mfma_f32_16x16x32_bf16 v[76:79], v[16:19], v[192:195], 0
	v_mfma_f32_16x16x32_bf16 v[68:71], v[24:27], v[192:195], 0
	s_waitcnt lgkmcnt(5)
	v_mfma_f32_16x16x32_bf16 v[60:63], v[16:19], v[200:203], 0
	v_mfma_f32_16x16x32_bf16 v[52:55], v[24:27], v[200:203], 0
	s_waitcnt lgkmcnt(3)
	v_mfma_f32_16x16x32_bf16 v[44:47], v[16:19], v[220:223], 0
	v_mfma_f32_16x16x32_bf16 v[36:39], v[24:27], v[220:223], 0
	s_waitcnt lgkmcnt(1)
	v_mfma_f32_16x16x32_bf16 v[12:15], v[16:19], v[228:231], 0
	v_mfma_f32_16x16x32_bf16 v[4:7], v[24:27], v[228:231], 0
	v_mfma_f32_16x16x32_bf16 v[76:79], v[20:23], v[196:199], v[76:79]
	v_mfma_f32_16x16x32_bf16 v[68:71], v[28:31], v[196:199], v[68:71]
	v_mfma_f32_16x16x32_bf16 v[60:63], v[20:23], v[204:207], v[60:63]
	v_mfma_f32_16x16x32_bf16 v[52:55], v[28:31], v[204:207], v[52:55]
	v_mfma_f32_16x16x32_bf16 v[44:47], v[20:23], v[224:227], v[44:47]
	v_mfma_f32_16x16x32_bf16 v[36:39], v[28:31], v[224:227], v[36:39]
	s_waitcnt lgkmcnt(0)
	v_mfma_f32_16x16x32_bf16 v[12:15], v[20:23], v[246:249], v[12:15]
	v_mfma_f32_16x16x32_bf16 v[4:7], v[28:31], v[246:249], v[4:7]
	s_setprio 0
	s_setprio 1
	v_mfma_f32_16x16x32_bf16 v[40:43], v[152:155], v[220:223], 0
	v_mfma_f32_16x16x32_bf16 v[32:35], v[168:171], v[220:223], 0
	v_mfma_f32_16x16x32_bf16 v[8:11], v[152:155], v[228:231], 0
	v_mfma_f32_16x16x32_bf16 v[0:3], v[168:171], v[228:231], 0
	v_mfma_f32_16x16x32_bf16 v[16:19], v[152:155], v[192:195], 0
	v_mfma_f32_16x16x32_bf16 v[20:23], v[168:171], v[192:195], 0
	v_mfma_f32_16x16x32_bf16 v[24:27], v[152:155], v[200:203], 0
	v_mfma_f32_16x16x32_bf16 v[28:31], v[168:171], v[200:203], 0
	v_mfma_f32_16x16x32_bf16 v[40:43], v[160:163], v[224:227], v[40:43]
	v_mfma_f32_16x16x32_bf16 v[32:35], v[176:179], v[224:227], v[32:35]
	v_mfma_f32_16x16x32_bf16 v[8:11], v[160:163], v[246:249], v[8:11]
	v_mfma_f32_16x16x32_bf16 v[0:3], v[176:179], v[246:249], v[0:3]
	v_mfma_f32_16x16x32_bf16 v[16:19], v[160:163], v[196:199], v[16:19]
	v_mfma_f32_16x16x32_bf16 v[20:23], v[176:179], v[196:199], v[20:23]
	v_mfma_f32_16x16x32_bf16 v[24:27], v[160:163], v[204:207], v[24:27]
	v_mfma_f32_16x16x32_bf16 v[28:31], v[176:179], v[204:207], v[28:31]
	s_setprio 0
	s_cmp_eq_u32 s101, 0
	s_cbranch_scc1 .Lhbp_p1_3
	s_barrier
.Lhbp_p1_3:
	v_add_u32_e32 v72, 0x18000, v83
	v_add_u32_e32 v80, 0x1c000, v83
	ds_read_b128 v[48:51], v72
	ds_read_b128 v[56:59], v72 offset:1024
	ds_read_b128 v[64:67], v72 offset:2048
	ds_read_b128 v[72:75], v72 offset:3072
	ds_read_b128 v[152:155], v80
	ds_read_b128 v[160:163], v80 offset:1024
	ds_read_b128 v[168:171], v80 offset:2048
	ds_read_b128 v[176:179], v80 offset:3072
	ds_read_b128 v[192:195], v245 offset:32768
	ds_read_b128 v[196:199], v245 offset:33792
	ds_read_b128 v[200:203], v245 offset:34816
	ds_read_b128 v[204:207], v245 offset:35840
	ds_read_b128 v[220:223], v245 offset:36864
	ds_read_b128 v[224:227], v245 offset:37888
	ds_read_b128 v[228:231], v245 offset:38912
	ds_read_b128 v[246:249], v245 offset:39936
	s_add_i32 s17, s17, 0x80000
	s_mov_b32 m0, s69
	s_nop 0
	buffer_load_dwordx4 v242, s[24:27], s17 offen lds
	s_nop 0
	s_mov_b32 m0, s70
	s_nop 0
	buffer_load_dwordx4 v243, s[24:27], s17 offen lds
	s_waitcnt vmcnt(8)
	s_waitcnt lgkmcnt(0)
	s_cmp_lg_u32 s101, 0
	s_cbranch_scc1 .Lhbp_p1_4
	s_barrier
.Lhbp_p1_4:
	s_setprio 1
	s_waitcnt lgkmcnt(7)
	v_mfma_f32_16x16x32_bf16 v[180:183], v[48:51], v[192:195], v[180:183]
	v_mfma_f32_16x16x32_bf16 v[164:167], v[64:67], v[192:195], v[164:167]
	s_waitcnt lgkmcnt(5)
	v_mfma_f32_16x16x32_bf16 v[148:151], v[48:51], v[200:203], v[148:151]
	v_mfma_f32_16x16x32_bf16 v[140:143], v[64:67], v[200:203], v[140:143]
	s_waitcnt lgkmcnt(3)
	v_mfma_f32_16x16x32_bf16 v[132:135], v[48:51], v[220:223], v[132:135]
	v_mfma_f32_16x16x32_bf16 v[124:127], v[64:67], v[220:223], v[124:127]
	s_waitcnt lgkmcnt(1)
	v_mfma_f32_16x16x32_bf16 v[116:119], v[48:51], v[228:231], v[116:119]
	v_mfma_f32_16x16x32_bf16 v[108:111], v[64:67], v[228:231], v[108:111]
	v_mfma_f32_16x16x32_bf16 v[180:183], v[56:59], v[196:199], v[180:183]
	v_mfma_f32_16x16x32_bf16 v[164:167], v[72:75], v[196:199], v[164:167]
	v_mfma_f32_16x16x32_bf16 v[148:151], v[56:59], v[204:207], v[148:151]
	v_mfma_f32_16x16x32_bf16 v[140:143], v[72:75], v[204:207], v[140:143]
	v_mfma_f32_16x16x32_bf16 v[132:135], v[56:59], v[224:227], v[132:135]
	v_mfma_f32_16x16x32_bf16 v[124:127], v[72:75], v[224:227], v[124:127]
	s_waitcnt lgkmcnt(0)
	v_mfma_f32_16x16x32_bf16 v[116:119], v[56:59], v[246:249], v[116:119]
	v_mfma_f32_16x16x32_bf16 v[108:111], v[72:75], v[246:249], v[108:111]
	s_setprio 0
	s_setprio 1
	v_mfma_f32_16x16x32_bf16 v[172:175], v[152:155], v[192:195], v[172:175]
	v_mfma_f32_16x16x32_bf16 v[156:159], v[168:171], v[192:195], v[156:159]
	v_mfma_f32_16x16x32_bf16 v[144:147], v[152:155], v[200:203], v[144:147]
	v_mfma_f32_16x16x32_bf16 v[136:139], v[168:171], v[200:203], v[136:139]
	v_mfma_f32_16x16x32_bf16 v[128:131], v[152:155], v[220:223], v[128:131]
	v_mfma_f32_16x16x32_bf16 v[120:123], v[168:171], v[220:223], v[120:123]
	v_mfma_f32_16x16x32_bf16 v[112:115], v[152:155], v[228:231], v[112:115]
	v_mfma_f32_16x16x32_bf16 v[104:107], v[168:171], v[228:231], v[104:107]
	v_mfma_f32_16x16x32_bf16 v[172:175], v[160:163], v[196:199], v[172:175]
	v_mfma_f32_16x16x32_bf16 v[156:159], v[176:179], v[196:199], v[156:159]
	v_mfma_f32_16x16x32_bf16 v[144:147], v[160:163], v[204:207], v[144:147]
	v_mfma_f32_16x16x32_bf16 v[136:139], v[176:179], v[204:207], v[136:139]
	v_mfma_f32_16x16x32_bf16 v[128:131], v[160:163], v[224:227], v[128:131]
	v_mfma_f32_16x16x32_bf16 v[120:123], v[176:179], v[224:227], v[120:123]
	v_mfma_f32_16x16x32_bf16 v[112:115], v[160:163], v[246:249], v[112:115]
	v_mfma_f32_16x16x32_bf16 v[104:107], v[176:179], v[246:249], v[104:107]
	s_setprio 0
	s_cmp_eq_u32 s101, 0
	s_cbranch_scc1 .Lhbp_p1_5
	s_barrier
.Lhbp_p1_5:
	ds_read_b128 v[192:195], v245 offset:49152
	ds_read_b128 v[196:199], v245 offset:50176
	ds_read_b128 v[200:203], v245 offset:51200
	ds_read_b128 v[204:207], v245 offset:52224
	ds_read_b128 v[220:223], v245 offset:53248
	ds_read_b128 v[224:227], v245 offset:54272
	ds_read_b128 v[228:231], v245 offset:55296
	ds_read_b128 v[246:249], v245 offset:56320
	s_or_b32 s17, s16, 0x4000
	s_mov_b32 m0, s73
	s_nop 0
	buffer_load_dwordx4 v242, s[56:59], s17 offen lds
	s_add_i32 s16, s16, 0x84000
	s_mov_b32 m0, s74
	s_nop 0
	buffer_load_dwordx4 v243, s[56:59], s17 offen lds
	s_nop 0
	s_mov_b32 m0, s77
	s_nop 0
	buffer_load_dwordx4 v242, s[56:59], s16 offen lds
	s_nop 0
	s_mov_b32 m0, s78
	s_nop 0
	buffer_load_dwordx4 v243, s[56:59], s16 offen lds
	s_nop 0
	s_mov_b32 m0, s75
	s_nop 0
	buffer_load_dwordx4 v242, s[24:27], s7 offen lds
	s_nop 0
	s_mov_b32 m0, s76
	s_nop 0
	buffer_load_dwordx4 v243, s[24:27], s7 offen lds
	s_waitcnt vmcnt(8)
	s_waitcnt lgkmcnt(0)
	s_cmp_lg_u32 s101, 0
	s_cbranch_scc1 .Lhbp_p1_6
	s_barrier
.Lhbp_p1_6:
	s_setprio 1
	s_waitcnt lgkmcnt(7)
	v_mfma_f32_16x16x32_bf16 v[76:79], v[48:51], v[192:195], v[76:79]
	v_mfma_f32_16x16x32_bf16 v[68:71], v[64:67], v[192:195], v[68:71]
	s_waitcnt lgkmcnt(5)
	v_mfma_f32_16x16x32_bf16 v[60:63], v[48:51], v[200:203], v[60:63]
	v_mfma_f32_16x16x32_bf16 v[52:55], v[64:67], v[200:203], v[52:55]
	s_waitcnt lgkmcnt(3)
	v_mfma_f32_16x16x32_bf16 v[44:47], v[48:51], v[220:223], v[44:47]
	v_mfma_f32_16x16x32_bf16 v[36:39], v[64:67], v[220:223], v[36:39]
	s_waitcnt lgkmcnt(1)
	v_mfma_f32_16x16x32_bf16 v[12:15], v[48:51], v[228:231], v[12:15]
	v_mfma_f32_16x16x32_bf16 v[4:7], v[64:67], v[228:231], v[4:7]
	v_mfma_f32_16x16x32_bf16 v[76:79], v[56:59], v[196:199], v[76:79]
	v_mfma_f32_16x16x32_bf16 v[68:71], v[72:75], v[196:199], v[68:71]
	v_mfma_f32_16x16x32_bf16 v[60:63], v[56:59], v[204:207], v[60:63]
	v_mfma_f32_16x16x32_bf16 v[52:55], v[72:75], v[204:207], v[52:55]
	v_mfma_f32_16x16x32_bf16 v[44:47], v[56:59], v[224:227], v[44:47]
	v_mfma_f32_16x16x32_bf16 v[36:39], v[72:75], v[224:227], v[36:39]
	s_waitcnt lgkmcnt(0)
	v_mfma_f32_16x16x32_bf16 v[12:15], v[56:59], v[246:249], v[12:15]
	v_mfma_f32_16x16x32_bf16 v[4:7], v[72:75], v[246:249], v[4:7]
	s_setprio 0
	s_setprio 1
	v_mfma_f32_16x16x32_bf16 v[16:19], v[152:155], v[192:195], v[16:19]
	v_mfma_f32_16x16x32_bf16 v[72:75], v[160:163], v[196:199], v[16:19]
	v_mfma_f32_16x16x32_bf16 v[16:19], v[168:171], v[192:195], v[20:23]
	v_mfma_f32_16x16x32_bf16 v[64:67], v[176:179], v[196:199], v[16:19]
	v_mfma_f32_16x16x32_bf16 v[16:19], v[152:155], v[200:203], v[24:27]
	v_mfma_f32_16x16x32_bf16 v[56:59], v[160:163], v[204:207], v[16:19]
	v_mfma_f32_16x16x32_bf16 v[16:19], v[168:171], v[200:203], v[28:31]
	v_mfma_f32_16x16x32_bf16 v[48:51], v[176:179], v[204:207], v[16:19]
	v_mfma_f32_16x16x32_bf16 v[16:19], v[152:155], v[220:223], v[40:43]
	v_mfma_f32_16x16x32_bf16 v[40:43], v[160:163], v[224:227], v[16:19]
	v_mfma_f32_16x16x32_bf16 v[16:19], v[168:171], v[220:223], v[32:35]
	v_mfma_f32_16x16x32_bf16 v[8:11], v[152:155], v[228:231], v[8:11]
	v_mfma_f32_16x16x32_bf16 v[0:3], v[168:171], v[228:231], v[0:3]
	v_mfma_f32_16x16x32_bf16 v[32:35], v[176:179], v[224:227], v[16:19]
	v_mfma_f32_16x16x32_bf16 v[8:11], v[160:163], v[246:249], v[8:11]
	v_mfma_f32_16x16x32_bf16 v[0:3], v[176:179], v[246:249], v[0:3]
	s_setprio 0
	s_cmp_eq_u32 s101, 0
	s_cbranch_scc1 .Lhbp_p1_7
	s_barrier
.Lhbp_p1_7:
	s_add_i32 s6, s6, 2
	s_add_i32 s4, s4, 0x8000
	s_add_i32 s5, s5, 0x8000
.LBB0_143:
	v_add_u32_e32 v28, 0x10000, v83
	v_add_u32_e32 v80, 0x14000, v83
	ds_read_b128 v[16:19], v28
	ds_read_b128 v[20:23], v28 offset:1024
	ds_read_b128 v[24:27], v28 offset:2048
	ds_read_b128 v[28:31], v28 offset:3072
	ds_read_b128 v[152:155], v80
	ds_read_b128 v[160:163], v80 offset:1024
	ds_read_b128 v[168:171], v80 offset:2048
	ds_read_b128 v[176:179], v80 offset:3072
	s_add_i32 s7, s4, 0xfff84000
	s_cmp_eq_u32 s6, 28
	s_cselect_b32 s17, s0, s7
	s_cselect_b32 s16, s1, s5
	s_or_b32 s7, s17, 0x4000
	ds_read_b128 v[192:195], v245
	ds_read_b128 v[196:199], v245 offset:1024
	ds_read_b128 v[200:203], v245 offset:2048
	ds_read_b128 v[204:207], v245 offset:3072
	ds_read_b128 v[220:223], v245 offset:4096
	ds_read_b128 v[224:227], v245 offset:5120
	ds_read_b128 v[228:231], v245 offset:6144
	ds_read_b128 v[246:249], v245 offset:7168
	s_mov_b32 m0, s79
	s_nop 0
	buffer_load_dwordx4 v242, s[24:27], s4 offen lds
	s_nop 0
	s_mov_b32 m0, s83
	s_nop 0
	buffer_load_dwordx4 v243, s[24:27], s4 offen lds
	s_waitcnt vmcnt(8)
	s_waitcnt lgkmcnt(0)
	s_cmp_lg_u32 s101, 0
	s_cbranch_scc1 .Lhb_p1_0
	s_barrier
.Lhb_p1_0:
	s_setprio 1
	s_waitcnt lgkmcnt(7)
	v_mfma_f32_16x16x32_bf16 v[180:183], v[16:19], v[192:195], v[180:183]
	v_mfma_f32_16x16x32_bf16 v[164:167], v[24:27], v[192:195], v[164:167]
	s_waitcnt lgkmcnt(5)
	v_mfma_f32_16x16x32_bf16 v[148:151], v[16:19], v[200:203], v[148:151]
	v_mfma_f32_16x16x32_bf16 v[140:143], v[24:27], v[200:203], v[140:143]
	s_waitcnt lgkmcnt(3)
	v_mfma_f32_16x16x32_bf16 v[132:135], v[16:19], v[220:223], v[132:135]
	v_mfma_f32_16x16x32_bf16 v[124:127], v[24:27], v[220:223], v[124:127]
	s_waitcnt lgkmcnt(1)
	v_mfma_f32_16x16x32_bf16 v[116:119], v[16:19], v[228:231], v[116:119]
	v_mfma_f32_16x16x32_bf16 v[108:111], v[24:27], v[228:231], v[108:111]
	v_mfma_f32_16x16x32_bf16 v[180:183], v[20:23], v[196:199], v[180:183]
	v_mfma_f32_16x16x32_bf16 v[164:167], v[28:31], v[196:199], v[164:167]
	v_mfma_f32_16x16x32_bf16 v[148:151], v[20:23], v[204:207], v[148:151]
	v_mfma_f32_16x16x32_bf16 v[140:143], v[28:31], v[204:207], v[140:143]
	v_mfma_f32_16x16x32_bf16 v[132:135], v[20:23], v[224:227], v[132:135]
	v_mfma_f32_16x16x32_bf16 v[124:127], v[28:31], v[224:227], v[124:127]
	s_waitcnt lgkmcnt(0)
	v_mfma_f32_16x16x32_bf16 v[116:119], v[20:23], v[246:249], v[116:119]
	v_mfma_f32_16x16x32_bf16 v[108:111], v[28:31], v[246:249], v[108:111]
	s_setprio 0
	s_setprio 1
	v_mfma_f32_16x16x32_bf16 v[172:175], v[152:155], v[192:195], v[172:175]
	v_mfma_f32_16x16x32_bf16 v[156:159], v[168:171], v[192:195], v[156:159]
	v_mfma_f32_16x16x32_bf16 v[144:147], v[152:155], v[200:203], v[144:147]
	v_mfma_f32_16x16x32_bf16 v[136:139], v[168:171], v[200:203], v[136:139]
	v_mfma_f32_16x16x32_bf16 v[128:131], v[152:155], v[220:223], v[128:131]
	v_mfma_f32_16x16x32_bf16 v[120:123], v[168:171], v[220:223], v[120:123]
	v_mfma_f32_16x16x32_bf16 v[112:115], v[152:155], v[228:231], v[112:115]
	v_mfma_f32_16x16x32_bf16 v[104:107], v[168:171], v[228:231], v[104:107]
	v_mfma_f32_16x16x32_bf16 v[172:175], v[160:163], v[196:199], v[172:175]
	v_mfma_f32_16x16x32_bf16 v[156:159], v[176:179], v[196:199], v[156:159]
	v_mfma_f32_16x16x32_bf16 v[144:147], v[160:163], v[204:207], v[144:147]
	v_mfma_f32_16x16x32_bf16 v[136:139], v[176:179], v[204:207], v[136:139]
	v_mfma_f32_16x16x32_bf16 v[128:131], v[160:163], v[224:227], v[128:131]
	v_mfma_f32_16x16x32_bf16 v[120:123], v[176:179], v[224:227], v[120:123]
	v_mfma_f32_16x16x32_bf16 v[112:115], v[160:163], v[246:249], v[112:115]
	v_mfma_f32_16x16x32_bf16 v[104:107], v[176:179], v[246:249], v[104:107]
	s_setprio 0
	s_cmp_eq_u32 s101, 0
	s_cbranch_scc1 .Lhb_p1_1
	s_barrier
.Lhb_p1_1:
	ds_read_b128 v[192:195], v245 offset:16384
	ds_read_b128 v[196:199], v245 offset:17408
	ds_read_b128 v[200:203], v245 offset:18432
	ds_read_b128 v[204:207], v245 offset:19456
	ds_read_b128 v[220:223], v245 offset:20480
	ds_read_b128 v[224:227], v245 offset:21504
	ds_read_b128 v[228:231], v245 offset:22528
	ds_read_b128 v[246:249], v245 offset:23552
	s_mov_b32 m0, s51
	s_nop 0
	buffer_load_dwordx4 v242, s[56:59], s16 offen lds
	s_add_i32 s18, s16, 0x80000
	s_mov_b32 m0, s52
	s_nop 0
	buffer_load_dwordx4 v243, s[56:59], s16 offen lds
	s_nop 0
	s_mov_b32 m0, s53
	s_nop 0
	buffer_load_dwordx4 v242, s[56:59], s18 offen lds
	s_nop 0
	s_mov_b32 m0, s55
	s_nop 0
	buffer_load_dwordx4 v243, s[56:59], s18 offen lds
	s_nop 0
	s_mov_b32 m0, s31
	s_nop 0
	buffer_load_dwordx4 v242, s[24:27], s17 offen lds
	s_nop 0
	s_mov_b32 m0, s68
	s_nop 0
	buffer_load_dwordx4 v243, s[24:27], s17 offen lds
	s_waitcnt vmcnt(8)
	s_waitcnt lgkmcnt(0)
	s_cmp_lg_u32 s101, 0
	s_cbranch_scc1 .Lhb_p1_2
	s_barrier
.Lhb_p1_2:
	s_setprio 1
	s_waitcnt lgkmcnt(7)
	v_mfma_f32_16x16x32_bf16 v[76:79], v[16:19], v[192:195], v[76:79]
	v_mfma_f32_16x16x32_bf16 v[68:71], v[24:27], v[192:195], v[68:71]
	s_waitcnt lgkmcnt(5)
	v_mfma_f32_16x16x32_bf16 v[60:63], v[16:19], v[200:203], v[60:63]
	v_mfma_f32_16x16x32_bf16 v[52:55], v[24:27], v[200:203], v[52:55]
	s_waitcnt lgkmcnt(3)
	v_mfma_f32_16x16x32_bf16 v[44:47], v[16:19], v[220:223], v[44:47]
	v_mfma_f32_16x16x32_bf16 v[36:39], v[24:27], v[220:223], v[36:39]
	s_waitcnt lgkmcnt(1)
	v_mfma_f32_16x16x32_bf16 v[12:15], v[16:19], v[228:231], v[12:15]
	v_mfma_f32_16x16x32_bf16 v[4:7], v[24:27], v[228:231], v[4:7]
	v_mfma_f32_16x16x32_bf16 v[76:79], v[20:23], v[196:199], v[76:79]
	v_mfma_f32_16x16x32_bf16 v[68:71], v[28:31], v[196:199], v[68:71]
	v_mfma_f32_16x16x32_bf16 v[60:63], v[20:23], v[204:207], v[60:63]
	v_mfma_f32_16x16x32_bf16 v[52:55], v[28:31], v[204:207], v[52:55]
	v_mfma_f32_16x16x32_bf16 v[44:47], v[20:23], v[224:227], v[44:47]
	v_mfma_f32_16x16x32_bf16 v[36:39], v[28:31], v[224:227], v[36:39]
	s_waitcnt lgkmcnt(0)
	v_mfma_f32_16x16x32_bf16 v[12:15], v[20:23], v[246:249], v[12:15]
	v_mfma_f32_16x16x32_bf16 v[4:7], v[28:31], v[246:249], v[4:7]
	s_setprio 0
	s_setprio 1
	v_mfma_f32_16x16x32_bf16 v[40:43], v[152:155], v[220:223], v[40:43]
	v_mfma_f32_16x16x32_bf16 v[32:35], v[168:171], v[220:223], v[32:35]
	v_mfma_f32_16x16x32_bf16 v[8:11], v[152:155], v[228:231], v[8:11]
	v_mfma_f32_16x16x32_bf16 v[0:3], v[168:171], v[228:231], v[0:3]
	v_mfma_f32_16x16x32_bf16 v[16:19], v[152:155], v[192:195], v[72:75]
	v_mfma_f32_16x16x32_bf16 v[20:23], v[168:171], v[192:195], v[64:67]
	v_mfma_f32_16x16x32_bf16 v[24:27], v[152:155], v[200:203], v[56:59]
	v_mfma_f32_16x16x32_bf16 v[28:31], v[168:171], v[200:203], v[48:51]
	v_mfma_f32_16x16x32_bf16 v[40:43], v[160:163], v[224:227], v[40:43]
	v_mfma_f32_16x16x32_bf16 v[32:35], v[176:179], v[224:227], v[32:35]
	v_mfma_f32_16x16x32_bf16 v[8:11], v[160:163], v[246:249], v[8:11]
	v_mfma_f32_16x16x32_bf16 v[0:3], v[176:179], v[246:249], v[0:3]
	v_mfma_f32_16x16x32_bf16 v[16:19], v[160:163], v[196:199], v[16:19]
	v_mfma_f32_16x16x32_bf16 v[20:23], v[176:179], v[196:199], v[20:23]
	v_mfma_f32_16x16x32_bf16 v[24:27], v[160:163], v[204:207], v[24:27]
	v_mfma_f32_16x16x32_bf16 v[28:31], v[176:179], v[204:207], v[28:31]
	s_setprio 0
	s_cmp_eq_u32 s101, 0
	s_cbranch_scc1 .Lhb_p1_3
	s_barrier

.Lhb_p1_7:
	s_add_i32 s6, s6, 2
	s_add_i32 s4, s4, 0x8000
	s_add_i32 s5, s5, 0x8000
	s_cmp_gt_u32 s6, 29
	s_cbranch_scc0 .LBB0_143
	s_and_b64 vcc, exec, s[10:11]
	s_cbranch_vccz .LBB0_146
	s_nop 0

.LBB0_367:
	v_readlane_b32 s0, v254, 23
	v_readlane_b32 s1, v254, 24
	s_andn2_b64 vcc, exec, s[0:1]
	s_cbranch_vccnz .LBB0_138
	s_nop 0
	s_branch .LBB0_138

.LBB0_580:
	s_andn2_b64 vcc, exec, s[0:1]
	v_readlane_b32 s0, v252, 47
	v_readlane_b32 s1, v252, 48
	s_nop 1
	v_cndmask_b32_e64 v0, 0, 1, s[0:1]
	v_cmp_ne_u32_e64 s[80:81], 1, v0
	s_cbranch_vccnz .LBB0_675
	v_mov_b32_e32 v0, v81
	s_and_b64 vcc, exec, s[80:81]
	v_mbcnt_lo_u32_b32 v0, -1, v0
	v_mbcnt_hi_u32_b32 v0, -1, v0
	v_add_u32_e32 v0, s69, v0
	s_nop 0
	v_readfirstlane_b32 s0, v0
	s_cbranch_vccnz .LBB0_603
	v_writelane_b32 v254, s80, 47
	v_lshlrev_b32_e32 v224, 4, v0
	s_mov_b32 s51, s59
	v_writelane_b32 v254, s81, 48
	v_add_u32_e32 v225, 0x2000, v224
	v_readlane_b32 s2, v254, 19
	v_readlane_b32 s3, v254, 20
	s_add_u32 s48, s2, 0x1e00000
	s_addc_u32 s4, s3, 0
	s_ashr_i32 s1, s0, 6
	s_lshl_b32 s2, s1, 10
	s_add_i32 s31, s2, 0x100
	s_and_b32 s49, s4, 0xffff
	s_add_i32 s34, s31, 0x10000
	v_readlane_b32 s4, v253, 11
	s_mov_b32 m0, s34
	s_nop 0
	buffer_load_dwordx4 v224, s[48:51], s4 offen lds
	s_add_i32 s55, s31, 0x12000
	s_mov_b32 m0, s55
	s_nop 0
	buffer_load_dwordx4 v225, s[48:51], s4 offen lds
	s_ashr_i32 s3, s0, 8
	s_add_i32 s72, s31, 0x14000
	v_readlane_b32 s4, v253, 5
	s_mov_b32 m0, s72
	s_nop 0
	buffer_load_dwordx4 v224, s[48:51], s4 offen lds
	s_add_i32 s73, s31, 0x16000
	s_add_i32 s74, s31, 0x2000
	s_add_i32 s75, s31, 0x4000
	s_add_i32 s76, s31, 0x6000
	s_mov_b32 m0, s73
	s_nop 0
	buffer_load_dwordx4 v225, s[48:51], s4 offen lds
	v_readlane_b32 s4, v254, 6
	s_cmp_eq_u32 s3, 1
	v_readlane_b32 s6, v254, 8
	v_readlane_b32 s7, v254, 9
	s_cselect_b64 s[10:11], -1, 0
	v_readlane_b32 s5, v254, 7
	s_mov_b32 s6, s26
	s_mov_b32 s7, s27
	v_readlane_b32 s8, v253, 9
	s_mov_b32 m0, s31
	s_nop 0
	buffer_load_dwordx4 v224, s[4:7], s8 offen lds
	v_writelane_b32 v254, s10, 45
	s_mov_b32 m0, s74
	s_nop 0
	buffer_load_dwordx4 v225, s[4:7], s8 offen lds
	v_readlane_b32 s8, v253, 7
	s_mov_b32 m0, s75
	s_nop 0
	buffer_load_dwordx4 v224, s[4:7], s8 offen lds
	s_cmp_lg_u32 s3, 1
	v_writelane_b32 v254, s11, 46
	v_writelane_b32 v254, s4, 6
	s_mov_b32 m0, s76
	s_nop 0
	buffer_load_dwordx4 v225, s[4:7], s8 offen lds
	s_cselect_b32 s100, 1, 0
	v_readlane_b32 s32, v253, 8
	v_readlane_b32 s98, v253, 10
	v_readlane_b32 s99, v253, 12
	s_nop 2
	s_add_i32 m0, s31, 0x18000
	s_nop 0
	buffer_load_dwordx4 v224, s[48:51], s32 offen lds
	s_add_i32 m0, s31, 0x1a000
	s_nop 0
	buffer_load_dwordx4 v225, s[48:51], s32 offen lds
	s_add_i32 m0, s31, 0x8000
	s_nop 0
	buffer_load_dwordx4 v224, s[4:7], s98 offen lds
	s_add_i32 m0, s31, 0xa000
	s_nop 0
	buffer_load_dwordx4 v225, s[4:7], s98 offen lds
	s_add_i32 m0, s31, 0x1c000
	s_nop 0
	buffer_load_dwordx4 v224, s[48:51], s99 offen lds
	s_add_i32 m0, s31, 0x1e000
	s_nop 0
	buffer_load_dwordx4 v225, s[48:51], s99 offen lds
	s_cmp_lg_u32 s100, 0
	s_nop 1
	v_writelane_b32 v254, s5, 7
	v_writelane_b32 v254, s6, 8
	v_writelane_b32 v254, s7, 9
	s_cbranch_scc1 .LBB0_584
	s_nop 0

.LBB0_594:
	v_add_u32_e32 v80, 0x10000, v226
	ds_read_b128 v[152:155], v80
	ds_read_b128 v[156:159], v80 offset:1024
	ds_read_b128 v[160:163], v80 offset:2048
	ds_read_b128 v[164:167], v80 offset:3072
	v_add_u32_e32 v80, 0x14000, v226
	ds_read_b128 v[168:171], v80
	ds_read_b128 v[172:175], v80 offset:1024
	ds_read_b128 v[176:179], v80 offset:2048
	ds_read_b128 v[180:183], v80 offset:3072
	s_add_i32 s97, s96, s39
	s_add_i32 s94, s97, 0x8000
	s_add_i32 s95, s93, s39
	s_cmp_eq_u32 s39, 0x78000
	s_cselect_b32 s36, vcc_lo, s94
	s_cselect_b32 s95, vcc_hi, s95
	s_or_b32 s94, s36, 0x4000
	ds_read_b128 v[184:187], v227
	ds_read_b128 v[188:191], v227 offset:1024
	ds_read_b128 v[192:195], v227 offset:2048
	ds_read_b128 v[196:199], v227 offset:3072
	ds_read_b128 v[200:203], v227 offset:4096
	ds_read_b128 v[204:207], v227 offset:5120
	ds_read_b128 v[228:231], v227 offset:6144
	ds_read_b128 v[240:243], v227 offset:7168
	s_add_i32 s97, s97, 0x84000
	s_mov_b32 m0, s85
	s_nop 0
	buffer_load_dwordx4 v224, s[60:63], s97 offen lds
	s_nop 0
	s_mov_b32 m0, s86
	s_nop 0
	buffer_load_dwordx4 v225, s[60:63], s97 offen lds
	s_waitcnt vmcnt(8)
	s_waitcnt lgkmcnt(0)
	s_cmp_lg_u32 s101, 0
	s_cbranch_scc1 .Lhb_p3_0
	s_barrier
.Lhb_p3_0:
	s_setprio 1
	s_waitcnt lgkmcnt(7)
	v_mfma_f32_16x16x32_bf16 v[148:151], v[152:155], v[184:187], v[148:151]
	v_mfma_f32_16x16x32_bf16 v[144:147], v[160:163], v[184:187], v[144:147]
	s_waitcnt lgkmcnt(5)
	v_mfma_f32_16x16x32_bf16 v[132:135], v[152:155], v[192:195], v[132:135]
	v_mfma_f32_16x16x32_bf16 v[128:131], v[160:163], v[192:195], v[128:131]
	s_waitcnt lgkmcnt(3)
	v_mfma_f32_16x16x32_bf16 v[116:119], v[152:155], v[200:203], v[116:119]
	v_mfma_f32_16x16x32_bf16 v[112:115], v[160:163], v[200:203], v[112:115]
	s_waitcnt lgkmcnt(1)
	v_mfma_f32_16x16x32_bf16 v[76:79], v[152:155], v[228:231], v[76:79]
	v_mfma_f32_16x16x32_bf16 v[72:75], v[160:163], v[228:231], v[72:75]
	v_mfma_f32_16x16x32_bf16 v[148:151], v[156:159], v[188:191], v[148:151]
	v_mfma_f32_16x16x32_bf16 v[144:147], v[164:167], v[188:191], v[144:147]
	v_mfma_f32_16x16x32_bf16 v[132:135], v[156:159], v[196:199], v[132:135]
	v_mfma_f32_16x16x32_bf16 v[128:131], v[164:167], v[196:199], v[128:131]
	v_mfma_f32_16x16x32_bf16 v[116:119], v[156:159], v[204:207], v[116:119]
	v_mfma_f32_16x16x32_bf16 v[112:115], v[164:167], v[204:207], v[112:115]
	s_waitcnt lgkmcnt(0)
	v_mfma_f32_16x16x32_bf16 v[76:79], v[156:159], v[240:243], v[76:79]
	v_mfma_f32_16x16x32_bf16 v[72:75], v[164:167], v[240:243], v[72:75]
	s_setprio 0
	s_setprio 1
	v_mfma_f32_16x16x32_bf16 v[140:143], v[168:171], v[184:187], v[140:143]
	v_mfma_f32_16x16x32_bf16 v[136:139], v[176:179], v[184:187], v[136:139]
	v_mfma_f32_16x16x32_bf16 v[124:127], v[168:171], v[192:195], v[124:127]
	v_mfma_f32_16x16x32_bf16 v[120:123], v[176:179], v[192:195], v[120:123]
	v_mfma_f32_16x16x32_bf16 v[108:111], v[168:171], v[200:203], v[108:111]
	v_mfma_f32_16x16x32_bf16 v[104:107], v[176:179], v[200:203], v[104:107]
	v_mfma_f32_16x16x32_bf16 v[68:71], v[168:171], v[228:231], v[68:71]
	v_mfma_f32_16x16x32_bf16 v[64:67], v[176:179], v[228:231], v[64:67]
	v_mfma_f32_16x16x32_bf16 v[140:143], v[172:175], v[188:191], v[140:143]
	v_mfma_f32_16x16x32_bf16 v[136:139], v[180:183], v[188:191], v[136:139]
	v_mfma_f32_16x16x32_bf16 v[124:127], v[172:175], v[196:199], v[124:127]
	v_mfma_f32_16x16x32_bf16 v[120:123], v[180:183], v[196:199], v[120:123]
	v_mfma_f32_16x16x32_bf16 v[108:111], v[172:175], v[204:207], v[108:111]
	v_mfma_f32_16x16x32_bf16 v[104:107], v[180:183], v[204:207], v[104:107]
	v_mfma_f32_16x16x32_bf16 v[68:71], v[172:175], v[240:243], v[68:71]
	v_mfma_f32_16x16x32_bf16 v[64:67], v[180:183], v[240:243], v[64:67]
	s_setprio 0
	s_cmp_eq_u32 s101, 0
	s_cbranch_scc1 .Lhb_p3_1
	s_barrier
.Lhb_p3_1:
	ds_read_b128 v[184:187], v227 offset:16384
	ds_read_b128 v[188:191], v227 offset:17408
	ds_read_b128 v[192:195], v227 offset:18432
	ds_read_b128 v[196:199], v227 offset:19456
	ds_read_b128 v[200:203], v227 offset:20480
	ds_read_b128 v[204:207], v227 offset:21504
	ds_read_b128 v[228:231], v227 offset:22528
	ds_read_b128 v[240:243], v227 offset:23552
	s_mov_b32 m0, s34
	s_nop 0
	buffer_load_dwordx4 v224, s[48:51], s95 offen lds
	s_add_i32 s97, s95, 0x80000
	s_mov_b32 m0, s55
	s_nop 0
	buffer_load_dwordx4 v225, s[48:51], s95 offen lds
	s_nop 0
	s_mov_b32 m0, s72
	s_nop 0
	buffer_load_dwordx4 v224, s[48:51], s97 offen lds
	s_nop 0
	s_mov_b32 m0, s73
	s_nop 0
	buffer_load_dwordx4 v225, s[48:51], s97 offen lds
	s_nop 0
	s_mov_b32 m0, s31
	s_nop 0
	buffer_load_dwordx4 v224, s[60:63], s36 offen lds
	s_nop 0
	s_mov_b32 m0, s74
	s_nop 0
	buffer_load_dwordx4 v225, s[60:63], s36 offen lds
	s_waitcnt vmcnt(8)
	s_waitcnt lgkmcnt(0)
	s_cmp_lg_u32 s101, 0
	s_cbranch_scc1 .Lhb_p3_2
	s_barrier
.Lhb_p3_2:
	s_setprio 1
	s_waitcnt lgkmcnt(7)
	v_mfma_f32_16x16x32_bf16 v[60:63], v[152:155], v[184:187], v[60:63]
	v_mfma_f32_16x16x32_bf16 v[56:59], v[160:163], v[184:187], v[56:59]
	s_waitcnt lgkmcnt(5)
	v_mfma_f32_16x16x32_bf16 v[44:47], v[152:155], v[192:195], v[44:47]
	v_mfma_f32_16x16x32_bf16 v[40:43], v[160:163], v[192:195], v[40:43]
	s_waitcnt lgkmcnt(3)
	v_mfma_f32_16x16x32_bf16 v[28:31], v[152:155], v[200:203], v[28:31]
	v_mfma_f32_16x16x32_bf16 v[24:27], v[160:163], v[200:203], v[24:27]
	s_waitcnt lgkmcnt(1)
	v_mfma_f32_16x16x32_bf16 v[12:15], v[152:155], v[228:231], v[12:15]
	v_mfma_f32_16x16x32_bf16 v[8:11], v[160:163], v[228:231], v[8:11]
	v_mfma_f32_16x16x32_bf16 v[60:63], v[156:159], v[188:191], v[60:63]
	v_mfma_f32_16x16x32_bf16 v[56:59], v[164:167], v[188:191], v[56:59]
	v_mfma_f32_16x16x32_bf16 v[44:47], v[156:159], v[196:199], v[44:47]
	v_mfma_f32_16x16x32_bf16 v[40:43], v[164:167], v[196:199], v[40:43]
	v_mfma_f32_16x16x32_bf16 v[28:31], v[156:159], v[204:207], v[28:31]
	v_mfma_f32_16x16x32_bf16 v[24:27], v[164:167], v[204:207], v[24:27]
	s_waitcnt lgkmcnt(0)
	v_mfma_f32_16x16x32_bf16 v[12:15], v[156:159], v[240:243], v[12:15]
	v_mfma_f32_16x16x32_bf16 v[8:11], v[164:167], v[240:243], v[8:11]
	s_setprio 0
	s_setprio 1
	v_mfma_f32_16x16x32_bf16 v[52:55], v[168:171], v[184:187], v[52:55]
	v_mfma_f32_16x16x32_bf16 v[48:51], v[176:179], v[184:187], v[48:51]
	v_mfma_f32_16x16x32_bf16 v[36:39], v[168:171], v[192:195], v[36:39]
	v_mfma_f32_16x16x32_bf16 v[32:35], v[176:179], v[192:195], v[32:35]
	v_mfma_f32_16x16x32_bf16 v[20:23], v[168:171], v[200:203], v[20:23]
	v_mfma_f32_16x16x32_bf16 v[16:19], v[176:179], v[200:203], v[16:19]
	v_mfma_f32_16x16x32_bf16 v[4:7], v[168:171], v[228:231], v[4:7]
	v_mfma_f32_16x16x32_bf16 v[0:3], v[176:179], v[228:231], v[0:3]
	v_mfma_f32_16x16x32_bf16 v[52:55], v[172:175], v[188:191], v[52:55]
	v_mfma_f32_16x16x32_bf16 v[48:51], v[180:183], v[188:191], v[48:51]
	v_mfma_f32_16x16x32_bf16 v[36:39], v[172:175], v[196:199], v[36:39]
	v_mfma_f32_16x16x32_bf16 v[32:35], v[180:183], v[196:199], v[32:35]
	v_mfma_f32_16x16x32_bf16 v[20:23], v[172:175], v[204:207], v[20:23]
	v_mfma_f32_16x16x32_bf16 v[16:19], v[180:183], v[204:207], v[16:19]
	v_mfma_f32_16x16x32_bf16 v[4:7], v[172:175], v[240:243], v[4:7]
	v_mfma_f32_16x16x32_bf16 v[0:3], v[180:183], v[240:243], v[0:3]
	s_setprio 0
	s_cmp_eq_u32 s101, 0
	s_cbranch_scc1 .Lhb_p3_3
	s_barrier
.Lhb_p3_3:
	v_add_u32_e32 v80, 0x18000, v226
	ds_read_b128 v[152:155], v80
	ds_read_b128 v[156:159], v80 offset:1024
	ds_read_b128 v[160:163], v80 offset:2048
	ds_read_b128 v[164:167], v80 offset:3072
	v_add_u32_e32 v80, 0x1c000, v226
	ds_read_b128 v[168:171], v80
	ds_read_b128 v[172:175], v80 offset:1024
	ds_read_b128 v[176:179], v80 offset:2048
	ds_read_b128 v[180:183], v80 offset:3072
	ds_read_b128 v[184:187], v227 offset:32768
	ds_read_b128 v[188:191], v227 offset:33792
	ds_read_b128 v[192:195], v227 offset:34816
	ds_read_b128 v[196:199], v227 offset:35840
	ds_read_b128 v[200:203], v227 offset:36864
	ds_read_b128 v[204:207], v227 offset:37888
	ds_read_b128 v[228:231], v227 offset:38912
	ds_read_b128 v[240:243], v227 offset:39936
	s_add_i32 s36, s36, 0x80000
	s_mov_b32 m0, s75
	s_nop 0
	buffer_load_dwordx4 v224, s[60:63], s36 offen lds
	s_nop 0
	s_mov_b32 m0, s76
	s_nop 0
	buffer_load_dwordx4 v225, s[60:63], s36 offen lds
	s_waitcnt vmcnt(8)
	s_waitcnt lgkmcnt(0)
	s_cmp_lg_u32 s101, 0
	s_cbranch_scc1 .Lhb_p3_4
	s_barrier

.Lhb_p3_5:
	ds_read_b128 v[184:187], v227 offset:49152
	ds_read_b128 v[188:191], v227 offset:50176
	ds_read_b128 v[192:195], v227 offset:51200
	ds_read_b128 v[196:199], v227 offset:52224
	ds_read_b128 v[200:203], v227 offset:53248
	ds_read_b128 v[204:207], v227 offset:54272
	ds_read_b128 v[228:231], v227 offset:55296
	ds_read_b128 v[240:243], v227 offset:56320
	s_or_b32 s36, s95, 0x4000
	s_mov_b32 m0, s77
	s_nop 0
	buffer_load_dwordx4 v224, s[48:51], s36 offen lds
	s_nop 0
	s_mov_b32 m0, s78
	s_nop 0
	buffer_load_dwordx4 v225, s[48:51], s36 offen lds
	s_add_i32 s36, s95, 0x84000
	s_mov_b32 m0, s83
	s_nop 0
	buffer_load_dwordx4 v224, s[48:51], s36 offen lds
	s_nop 0
	s_mov_b32 m0, s84
	s_nop 0
	buffer_load_dwordx4 v225, s[48:51], s36 offen lds
	s_nop 0
	s_mov_b32 m0, s79
	s_nop 0
	buffer_load_dwordx4 v224, s[60:63], s94 offen lds
	s_nop 0
	s_mov_b32 m0, s82
	s_nop 0
	buffer_load_dwordx4 v225, s[60:63], s94 offen lds
	s_waitcnt vmcnt(8)
	s_waitcnt lgkmcnt(0)
	s_cmp_lg_u32 s101, 0
	s_cbranch_scc1 .Lhb_p3_6
	s_barrier

.Lhb_p3_7:
	s_add_i32 s38, s38, 2
	s_add_i32 s39, s39, 0x8000
	s_cmp_gt_u32 s38, 29
	s_cbranch_scc1 .LBB0_597

.LBB0_597:
	v_readlane_b32 s4, v254, 43
	v_readlane_b32 s5, v254, 44
	s_and_b64 vcc, exec, s[4:5]
	s_cbranch_vccz .LBB0_599
	s_nop 0
.LBB0_599:
	v_readlane_b32 s8, v252, 45
	s_add_u32 s4, s8, s91
	v_readlane_b32 s9, v252, 46
	s_addc_u32 s5, s9, 0
	s_nop 0
	v_lshl_add_u64 v[82:83], s[4:5], 0, v[220:221]
	global_load_dwordx4 v[228:231], v[82:83], off
	s_add_u32 s4, s8, s90
	s_addc_u32 s5, s9, 0
	s_add_u32 s6, s8, s88
	v_lshl_add_u64 v[82:83], s[4:5], 0, v[220:221]
	global_load_dwordx4 v[240:243], v[82:83], off
	s_addc_u32 s7, s9, 0
	s_add_u32 s4, s8, s81
	v_lshl_add_u64 v[82:83], s[6:7], 0, v[220:221]
	global_load_dwordx4 v[204:207], v[82:83], off
	s_addc_u32 s5, s9, 0
	s_add_u32 s6, s8, s80
	v_lshl_add_u64 v[82:83], s[4:5], 0, v[220:221]
	global_load_dwordx4 v[200:203], v[82:83], off
	s_addc_u32 s7, s9, 0
	s_add_u32 s4, s8, s89
	v_lshl_add_u64 v[82:83], s[6:7], 0, v[220:221]
	global_load_dwordx4 v[196:199], v[82:83], off
	s_addc_u32 s5, s9, 0
	s_add_u32 s6, s8, s33
	v_lshl_add_u64 v[82:83], s[4:5], 0, v[220:221]
	global_load_dwordx4 v[192:195], v[82:83], off
	s_addc_u32 s7, s9, 0
	s_add_u32 s4, s8, s3
	v_lshl_add_u64 v[82:83], s[6:7], 0, v[220:221]
	global_load_dwordx4 v[188:191], v[82:83], off
	s_addc_u32 s5, s9, 0
	s_add_u32 s2, s8, s2
	v_lshl_add_u64 v[82:83], s[4:5], 0, v[220:221]
	global_load_dwordx4 v[184:187], v[82:83], off
	s_addc_u32 s3, s9, 0
	s_add_u32 s4, s8, s1
	v_lshl_add_u64 v[82:83], s[2:3], 0, v[220:221]
	global_load_dwordx4 v[180:183], v[82:83], off
	s_addc_u32 s5, s9, 0
	s_add_u32 s0, s8, s0
	v_lshl_add_u64 v[82:83], s[4:5], 0, v[220:221]
	global_load_dwordx4 v[176:179], v[82:83], off
	s_addc_u32 s1, s9, 0
	s_add_u32 s2, s8, s37
	v_lshl_add_u64 v[82:83], s[0:1], 0, v[220:221]
	global_load_dwordx4 v[172:175], v[82:83], off
	s_addc_u32 s3, s9, 0
	v_readlane_b32 s0, v254, 41
	v_lshl_add_u64 v[82:83], s[2:3], 0, v[220:221]
	global_load_dwordx4 v[168:171], v[82:83], off
	s_add_u32 s0, s8, s0
	s_addc_u32 s1, s9, 0
	v_readlane_b32 s2, v254, 39
	v_lshl_add_u64 v[82:83], s[0:1], 0, v[220:221]
	global_load_dwordx4 v[164:167], v[82:83], off
	s_add_u32 s2, s8, s2
	s_addc_u32 s3, s9, 0
	v_readlane_b32 s0, v254, 37
	v_lshl_add_u64 v[82:83], s[2:3], 0, v[220:221]
	global_load_dwordx4 v[160:163], v[82:83], off
	s_add_u32 s0, s8, s0
	s_addc_u32 s1, s9, 0
	v_readlane_b32 s2, v254, 35
	v_lshl_add_u64 v[82:83], s[0:1], 0, v[220:221]
	global_load_dwordx4 v[156:159], v[82:83], off
	s_add_u32 s2, s8, s2
	s_addc_u32 s3, s9, 0
	s_lshl_b32 s0, s92, 16
	v_lshl_add_u64 v[82:83], s[2:3], 0, v[220:221]
	global_load_dwordx4 v[152:155], v[82:83], off
	v_readlane_b32 s1, v254, 33
	s_add_i32 s0, s1, s0
	v_readlane_b32 s8, v254, 10
	s_waitcnt vmcnt(15)
	v_lshlrev_b32_e32 v82, 16, v228
	v_and_b32_e32 v83, 0xffff0000, v228
	v_lshlrev_b32_e32 v208, 16, v229
	v_and_b32_e32 v209, 0xffff0000, v229
	s_add_u32 s2, s8, s0
	v_readlane_b32 s6, v252, 49
	v_pk_mul_f32 v[150:151], v[150:151], v[208:209]
	v_pk_mul_f32 v[82:83], v[148:149], v[82:83]
	v_lshlrev_b32_e32 v148, 16, v230
	v_and_b32_e32 v149, 0xffff0000, v230
	v_lshlrev_b32_e32 v208, 16, v231
	v_and_b32_e32 v209, 0xffff0000, v231
	s_addc_u32 s3, s6, 0
	v_pk_mul_f32 v[208:209], v[146:147], v[208:209]
	v_pk_mul_f32 v[146:147], v[144:145], v[148:149]
	s_mov_b64 s[4:5], s[2:3]
	v_cvt_pk_bf16_f32 v144, v82, v83
	v_cvt_pk_bf16_f32 v145, v150, v151
	v_cvt_pk_bf16_f32 v146, v146, v147
	v_cvt_pk_bf16_f32 v147, v208, v209
	s_or_b32 s1, s0, 0x8000
	v_lshl_add_u64 v[82:83], s[4:5], 0, v[222:223]
	global_store_dwordx4 v[82:83], v[144:147], off
	s_waitcnt vmcnt(15)
	v_lshlrev_b32_e32 v82, 16, v240
	v_and_b32_e32 v83, 0xffff0000, v240
	v_lshlrev_b32_e32 v144, 16, v241
	v_and_b32_e32 v145, 0xffff0000, v241
	v_pk_mul_f32 v[142:143], v[142:143], v[144:145]
	v_pk_mul_f32 v[82:83], v[140:141], v[82:83]
	v_lshlrev_b32_e32 v140, 16, v242
	v_and_b32_e32 v141, 0xffff0000, v242
	v_lshlrev_b32_e32 v144, 16, v243
	v_and_b32_e32 v145, 0xffff0000, v243
	s_add_u32 s4, s8, s1
	v_pk_mul_f32 v[144:145], v[138:139], v[144:145]
	v_pk_mul_f32 v[138:139], v[136:137], v[140:141]
	s_addc_u32 s5, s6, 0
	v_cvt_pk_bf16_f32 v136, v82, v83
	v_cvt_pk_bf16_f32 v137, v142, v143
	v_cvt_pk_bf16_f32 v138, v138, v139
	v_cvt_pk_bf16_f32 v139, v144, v145
	s_add_u32 s2, s2, 0x800
	v_lshl_add_u64 v[82:83], s[4:5], 0, v[222:223]
	global_store_dwordx4 v[82:83], v[136:139], off
	s_waitcnt vmcnt(15)
	v_lshlrev_b32_e32 v82, 16, v204
	v_and_b32_e32 v83, 0xffff0000, v204
	v_lshlrev_b32_e32 v136, 16, v205
	v_and_b32_e32 v137, 0xffff0000, v205
	v_pk_mul_f32 v[134:135], v[134:135], v[136:137]
	v_pk_mul_f32 v[82:83], v[132:133], v[82:83]
	v_lshlrev_b32_e32 v132, 16, v206
	v_and_b32_e32 v133, 0xffff0000, v206
	v_lshlrev_b32_e32 v136, 16, v207
	v_and_b32_e32 v137, 0xffff0000, v207
	v_pk_mul_f32 v[136:137], v[130:131], v[136:137]
	v_pk_mul_f32 v[130:131], v[128:129], v[132:133]
	s_addc_u32 s3, s3, 0
	v_cvt_pk_bf16_f32 v128, v82, v83
	v_cvt_pk_bf16_f32 v129, v134, v135
	v_cvt_pk_bf16_f32 v130, v130, v131
	v_cvt_pk_bf16_f32 v131, v136, v137
	s_or_b32 s1, s0, 0x8800
	v_lshl_add_u64 v[82:83], s[2:3], 0, v[222:223]
	global_store_dwordx4 v[82:83], v[128:131], off
	s_waitcnt vmcnt(15)
	v_lshlrev_b32_e32 v82, 16, v200
	v_and_b32_e32 v83, 0xffff0000, v200
	v_lshlrev_b32_e32 v128, 16, v201
	v_and_b32_e32 v129, 0xffff0000, v201
	v_pk_mul_f32 v[126:127], v[126:127], v[128:129]
	v_pk_mul_f32 v[82:83], v[124:125], v[82:83]
	v_lshlrev_b32_e32 v124, 16, v202
	v_and_b32_e32 v125, 0xffff0000, v202
	v_lshlrev_b32_e32 v128, 16, v203
	v_and_b32_e32 v129, 0xffff0000, v203
	s_add_u32 s2, s8, s1
	v_pk_mul_f32 v[128:129], v[122:123], v[128:129]
	v_pk_mul_f32 v[122:123], v[120:121], v[124:125]
	s_addc_u32 s3, s6, 0
	v_cvt_pk_bf16_f32 v120, v82, v83
	v_cvt_pk_bf16_f32 v121, v126, v127
	v_cvt_pk_bf16_f32 v122, v122, v123
	v_cvt_pk_bf16_f32 v123, v128, v129
	s_or_b32 s1, s0, 0x1000
	v_lshl_add_u64 v[82:83], s[2:3], 0, v[222:223]
	global_store_dwordx4 v[82:83], v[120:123], off
	s_waitcnt vmcnt(15)
	v_lshlrev_b32_e32 v82, 16, v196
	v_and_b32_e32 v83, 0xffff0000, v196
	v_lshlrev_b32_e32 v120, 16, v197
	v_and_b32_e32 v121, 0xffff0000, v197
	v_pk_mul_f32 v[118:119], v[118:119], v[120:121]
	v_pk_mul_f32 v[82:83], v[116:117], v[82:83]
	v_lshlrev_b32_e32 v116, 16, v198
	v_and_b32_e32 v117, 0xffff0000, v198
	v_lshlrev_b32_e32 v120, 16, v199
	v_and_b32_e32 v121, 0xffff0000, v199
	s_add_u32 s2, s8, s1
	v_pk_mul_f32 v[120:121], v[114:115], v[120:121]
	v_pk_mul_f32 v[114:115], v[112:113], v[116:117]
	s_addc_u32 s3, s6, 0
	v_cvt_pk_bf16_f32 v112, v82, v83
	v_cvt_pk_bf16_f32 v113, v118, v119
	v_cvt_pk_bf16_f32 v114, v114, v115
	v_cvt_pk_bf16_f32 v115, v120, v121
	s_or_b32 s1, s0, 0x9000
	v_lshl_add_u64 v[82:83], s[2:3], 0, v[222:223]
	global_store_dwordx4 v[82:83], v[112:115], off
	s_waitcnt vmcnt(15)
	v_lshlrev_b32_e32 v82, 16, v192
	v_and_b32_e32 v83, 0xffff0000, v192
	v_lshlrev_b32_e32 v112, 16, v193
	v_and_b32_e32 v113, 0xffff0000, v193
	v_pk_mul_f32 v[110:111], v[110:111], v[112:113]
	v_pk_mul_f32 v[82:83], v[108:109], v[82:83]
	v_lshlrev_b32_e32 v108, 16, v194
	v_and_b32_e32 v109, 0xffff0000, v194
	v_lshlrev_b32_e32 v112, 16, v195
	v_and_b32_e32 v113, 0xffff0000, v195
	s_add_u32 s2, s8, s1
	v_pk_mul_f32 v[112:113], v[106:107], v[112:113]
	v_pk_mul_f32 v[106:107], v[104:105], v[108:109]
	s_addc_u32 s3, s6, 0
	v_cvt_pk_bf16_f32 v104, v82, v83
	v_cvt_pk_bf16_f32 v105, v110, v111
	v_cvt_pk_bf16_f32 v106, v106, v107
	v_cvt_pk_bf16_f32 v107, v112, v113
	s_or_b32 s1, s0, 0x1800
	v_lshl_add_u64 v[82:83], s[2:3], 0, v[222:223]
	global_store_dwordx4 v[82:83], v[104:107], off
	s_waitcnt vmcnt(15)
	v_lshlrev_b32_e32 v82, 16, v188
	v_and_b32_e32 v83, 0xffff0000, v188
	v_lshlrev_b32_e32 v104, 16, v189
	v_and_b32_e32 v105, 0xffff0000, v189
	v_pk_mul_f32 v[78:79], v[78:79], v[104:105]
	v_pk_mul_f32 v[76:77], v[76:77], v[82:83]
	v_lshlrev_b32_e32 v82, 16, v190
	v_and_b32_e32 v83, 0xffff0000, v190
	v_lshlrev_b32_e32 v104, 16, v191
	v_and_b32_e32 v105, 0xffff0000, v191
	s_add_u32 s2, s8, s1
	v_pk_mul_f32 v[104:105], v[74:75], v[104:105]
	v_pk_mul_f32 v[74:75], v[72:73], v[82:83]
	s_addc_u32 s3, s6, 0
	v_cvt_pk_bf16_f32 v72, v76, v77
	v_cvt_pk_bf16_f32 v73, v78, v79
	v_cvt_pk_bf16_f32 v74, v74, v75
	v_cvt_pk_bf16_f32 v75, v104, v105
	s_or_b32 s1, s0, 0x9800
	v_lshl_add_u64 v[76:77], s[2:3], 0, v[222:223]
	global_store_dwordx4 v[76:77], v[72:75], off
	s_add_u32 s2, s8, s1
	s_addc_u32 s3, s6, 0
	s_waitcnt vmcnt(15)
	v_lshlrev_b32_e32 v72, 16, v184
	v_and_b32_e32 v73, 0xffff0000, v184
	v_lshlrev_b32_e32 v74, 16, v185
	v_and_b32_e32 v75, 0xffff0000, v185
	v_pk_mul_f32 v[70:71], v[70:71], v[74:75]
	v_pk_mul_f32 v[68:69], v[68:69], v[72:73]
	v_lshlrev_b32_e32 v72, 16, v186
	v_and_b32_e32 v73, 0xffff0000, v186
	v_lshlrev_b32_e32 v74, 16, v187
	v_and_b32_e32 v75, 0xffff0000, v187
	v_pk_mul_f32 v[74:75], v[66:67], v[74:75]
	v_pk_mul_f32 v[66:67], v[64:65], v[72:73]
	v_cvt_pk_bf16_f32 v64, v68, v69
	v_cvt_pk_bf16_f32 v65, v70, v71
	v_cvt_pk_bf16_f32 v66, v66, v67
	v_cvt_pk_bf16_f32 v67, v74, v75
	s_add_i32 s1, s0, 0x80000
	v_lshl_add_u64 v[68:69], s[2:3], 0, v[222:223]
	global_store_dwordx4 v[68:69], v[64:67], off
	s_add_u32 s2, s8, s1
	s_addc_u32 s3, s6, 0
	s_waitcnt vmcnt(15)
	v_lshlrev_b32_e32 v64, 16, v180
	v_and_b32_e32 v65, 0xffff0000, v180
	v_lshlrev_b32_e32 v66, 16, v181
	v_and_b32_e32 v67, 0xffff0000, v181
	v_pk_mul_f32 v[62:63], v[62:63], v[66:67]
	v_pk_mul_f32 v[60:61], v[60:61], v[64:65]
	v_lshlrev_b32_e32 v64, 16, v182
	v_and_b32_e32 v65, 0xffff0000, v182
	v_lshlrev_b32_e32 v66, 16, v183
	v_and_b32_e32 v67, 0xffff0000, v183
	v_pk_mul_f32 v[66:67], v[58:59], v[66:67]
	v_pk_mul_f32 v[58:59], v[56:57], v[64:65]
	v_cvt_pk_bf16_f32 v56, v60, v61
	v_cvt_pk_bf16_f32 v57, v62, v63
	v_cvt_pk_bf16_f32 v58, v58, v59
	v_cvt_pk_bf16_f32 v59, v66, v67
	s_add_i32 s1, s0, 0x88000
	v_lshl_add_u64 v[60:61], s[2:3], 0, v[222:223]
	global_store_dwordx4 v[60:61], v[56:59], off
	s_add_u32 s2, s8, s1
	s_addc_u32 s3, s6, 0
	s_waitcnt vmcnt(15)
	v_lshlrev_b32_e32 v56, 16, v176
	v_and_b32_e32 v57, 0xffff0000, v176
	v_lshlrev_b32_e32 v58, 16, v177
	v_and_b32_e32 v59, 0xffff0000, v177
	v_pk_mul_f32 v[54:55], v[54:55], v[58:59]
	v_pk_mul_f32 v[52:53], v[52:53], v[56:57]
	v_lshlrev_b32_e32 v56, 16, v178
	v_and_b32_e32 v57, 0xffff0000, v178
	v_lshlrev_b32_e32 v58, 16, v179
	v_and_b32_e32 v59, 0xffff0000, v179
	v_pk_mul_f32 v[58:59], v[50:51], v[58:59]
	v_pk_mul_f32 v[50:51], v[48:49], v[56:57]
	v_cvt_pk_bf16_f32 v48, v52, v53
	v_cvt_pk_bf16_f32 v49, v54, v55
	v_cvt_pk_bf16_f32 v50, v50, v51
	v_cvt_pk_bf16_f32 v51, v58, v59
	s_add_i32 s1, s0, 0x80800
	v_lshl_add_u64 v[52:53], s[2:3], 0, v[222:223]
	global_store_dwordx4 v[52:53], v[48:51], off
	s_add_u32 s2, s8, s1
	s_addc_u32 s3, s6, 0
	s_waitcnt vmcnt(15)
	v_lshlrev_b32_e32 v48, 16, v172
	v_and_b32_e32 v49, 0xffff0000, v172
	v_lshlrev_b32_e32 v50, 16, v173
	v_and_b32_e32 v51, 0xffff0000, v173
	v_pk_mul_f32 v[46:47], v[46:47], v[50:51]
	v_pk_mul_f32 v[44:45], v[44:45], v[48:49]
	v_lshlrev_b32_e32 v48, 16, v174
	v_and_b32_e32 v49, 0xffff0000, v174
	v_lshlrev_b32_e32 v50, 16, v175
	v_and_b32_e32 v51, 0xffff0000, v175
	v_pk_mul_f32 v[50:51], v[42:43], v[50:51]
	v_pk_mul_f32 v[42:43], v[40:41], v[48:49]
	v_cvt_pk_bf16_f32 v40, v44, v45
	v_cvt_pk_bf16_f32 v41, v46, v47
	v_cvt_pk_bf16_f32 v42, v42, v43
	v_cvt_pk_bf16_f32 v43, v50, v51
	s_add_i32 s1, s0, 0x88800
	v_lshl_add_u64 v[44:45], s[2:3], 0, v[222:223]
	global_store_dwordx4 v[44:45], v[40:43], off
	s_add_u32 s2, s8, s1
	s_addc_u32 s3, s6, 0
	s_waitcnt vmcnt(15)
	v_lshlrev_b32_e32 v40, 16, v168
	v_and_b32_e32 v41, 0xffff0000, v168
	v_lshlrev_b32_e32 v42, 16, v169
	v_and_b32_e32 v43, 0xffff0000, v169
	v_pk_mul_f32 v[38:39], v[38:39], v[42:43]
	v_pk_mul_f32 v[36:37], v[36:37], v[40:41]
	v_lshlrev_b32_e32 v40, 16, v170
	v_and_b32_e32 v41, 0xffff0000, v170
	v_lshlrev_b32_e32 v42, 16, v171
	v_and_b32_e32 v43, 0xffff0000, v171
	v_pk_mul_f32 v[42:43], v[34:35], v[42:43]
	v_pk_mul_f32 v[34:35], v[32:33], v[40:41]
	v_cvt_pk_bf16_f32 v32, v36, v37
	v_cvt_pk_bf16_f32 v33, v38, v39
	v_cvt_pk_bf16_f32 v34, v34, v35
	v_cvt_pk_bf16_f32 v35, v42, v43
	s_add_i32 s1, s0, 0x81000
	v_lshl_add_u64 v[36:37], s[2:3], 0, v[222:223]
	global_store_dwordx4 v[36:37], v[32:35], off
	s_add_u32 s2, s8, s1
	s_addc_u32 s3, s6, 0
	s_waitcnt vmcnt(15)
	v_lshlrev_b32_e32 v32, 16, v164
	v_and_b32_e32 v33, 0xffff0000, v164
	v_lshlrev_b32_e32 v34, 16, v165
	v_and_b32_e32 v35, 0xffff0000, v165
	v_pk_mul_f32 v[30:31], v[30:31], v[34:35]
	v_pk_mul_f32 v[28:29], v[28:29], v[32:33]
	v_lshlrev_b32_e32 v32, 16, v166
	v_and_b32_e32 v33, 0xffff0000, v166
	v_lshlrev_b32_e32 v34, 16, v167
	v_and_b32_e32 v35, 0xffff0000, v167
	v_pk_mul_f32 v[34:35], v[26:27], v[34:35]
	v_pk_mul_f32 v[26:27], v[24:25], v[32:33]
	v_cvt_pk_bf16_f32 v24, v28, v29
	v_cvt_pk_bf16_f32 v25, v30, v31
	v_cvt_pk_bf16_f32 v26, v26, v27
	v_cvt_pk_bf16_f32 v27, v34, v35
	s_add_i32 s1, s0, 0x89000
	v_lshl_add_u64 v[28:29], s[2:3], 0, v[222:223]
	global_store_dwordx4 v[28:29], v[24:27], off
	s_add_u32 s2, s8, s1
	s_addc_u32 s3, s6, 0
	s_waitcnt vmcnt(15)
	v_lshlrev_b32_e32 v24, 16, v160
	v_and_b32_e32 v25, 0xffff0000, v160
	v_lshlrev_b32_e32 v26, 16, v161
	v_and_b32_e32 v27, 0xffff0000, v161
	v_pk_mul_f32 v[22:23], v[22:23], v[26:27]
	v_pk_mul_f32 v[20:21], v[20:21], v[24:25]
	v_lshlrev_b32_e32 v24, 16, v162
	v_and_b32_e32 v25, 0xffff0000, v162
	v_lshlrev_b32_e32 v26, 16, v163
	v_and_b32_e32 v27, 0xffff0000, v163
	v_pk_mul_f32 v[26:27], v[18:19], v[26:27]
	v_pk_mul_f32 v[18:19], v[16:17], v[24:25]
	v_cvt_pk_bf16_f32 v16, v20, v21
	v_cvt_pk_bf16_f32 v17, v22, v23
	v_cvt_pk_bf16_f32 v18, v18, v19
	v_cvt_pk_bf16_f32 v19, v26, v27
	s_add_i32 s1, s0, 0x81800
	v_lshl_add_u64 v[20:21], s[2:3], 0, v[222:223]
	global_store_dwordx4 v[20:21], v[16:19], off
	s_add_u32 s2, s8, s1
	s_addc_u32 s3, s6, 0
	s_waitcnt vmcnt(15)
	v_lshlrev_b32_e32 v16, 16, v156
	v_and_b32_e32 v17, 0xffff0000, v156
	v_lshlrev_b32_e32 v18, 16, v157
	v_and_b32_e32 v19, 0xffff0000, v157
	v_pk_mul_f32 v[14:15], v[14:15], v[18:19]
	v_pk_mul_f32 v[12:13], v[12:13], v[16:17]
	v_lshlrev_b32_e32 v16, 16, v158
	v_and_b32_e32 v17, 0xffff0000, v158
	v_lshlrev_b32_e32 v18, 16, v159
	v_and_b32_e32 v19, 0xffff0000, v159
	v_pk_mul_f32 v[18:19], v[10:11], v[18:19]
	v_pk_mul_f32 v[10:11], v[8:9], v[16:17]
	s_add_i32 s0, s0, 0x89800
	v_cvt_pk_bf16_f32 v8, v12, v13
	v_cvt_pk_bf16_f32 v9, v14, v15
	v_cvt_pk_bf16_f32 v10, v10, v11
	v_cvt_pk_bf16_f32 v11, v18, v19
	s_add_u32 s0, s8, s0
	v_lshl_add_u64 v[12:13], s[2:3], 0, v[222:223]
	global_store_dwordx4 v[12:13], v[8:11], off
	s_addc_u32 s1, s6, 0
	s_mov_b64 s[4:5], -1
	s_waitcnt vmcnt(15)
	v_lshlrev_b32_e32 v8, 16, v152
	v_and_b32_e32 v9, 0xffff0000, v152
	v_lshlrev_b32_e32 v10, 16, v153
	v_and_b32_e32 v11, 0xffff0000, v153
	v_pk_mul_f32 v[6:7], v[6:7], v[10:11]
	v_pk_mul_f32 v[4:5], v[4:5], v[8:9]
	v_lshlrev_b32_e32 v8, 16, v154
	v_and_b32_e32 v9, 0xffff0000, v154
	v_lshlrev_b32_e32 v10, 16, v155
	v_and_b32_e32 v11, 0xffff0000, v155
	v_pk_mul_f32 v[10:11], v[2:3], v[10:11]
	v_pk_mul_f32 v[2:3], v[0:1], v[8:9]
	v_cvt_pk_bf16_f32 v0, v4, v5
	v_lshl_add_u64 v[4:5], s[0:1], 0, v[222:223]
	v_readlane_b32 s0, v254, 23
	v_readlane_b32 s1, v254, 24
	v_cvt_pk_bf16_f32 v1, v6, v7
	v_cvt_pk_bf16_f32 v2, v2, v3
	v_cvt_pk_bf16_f32 v3, v10, v11
	s_andn2_b64 vcc, exec, s[0:1]
	v_readlane_b32 s6, v254, 25
	v_readlane_b32 s3, v254, 27
	v_readlane_b32 s9, v254, 11
	v_readlane_b32 s10, v254, 12
	v_readlane_b32 s11, v254, 13
	global_store_dwordx4 v[4:5], v[0:3], off
	s_cbranch_vccnz .LBB0_586
	v_readlane_b32 s0, v254, 45
	v_readlane_b32 s1, v254, 46
	s_andn2_b64 vcc, exec, s[0:1]
	s_cbranch_vccnz .LBB0_585
	s_nop 0
	s_branch .LBB0_585

.LBB0_603:
	v_readfirstlane_b32 s100, v240
	v_readlane_b32 s98, v254, 19
	v_readlane_b32 s99, v254, 20
	v_readlane_b32 s32, v253, 36
	v_readlane_b32 vcc_lo, v253, 31
	s_lshr_b32 s100, s100, 7
	s_cmp_eq_u32 s100, 1
	s_cselect_b32 s32, vcc_lo, s32
	v_readlane_b32 vcc_lo, v253, 33
	s_cmp_eq_u32 s100, 2
	s_cselect_b32 s32, vcc_lo, s32
	v_readlane_b32 vcc_lo, v253, 37
	s_cmp_eq_u32 s100, 3
	s_cselect_b32 s32, vcc_lo, s32
	s_add_u32 s98, s98, 0x2600000
	s_addc_u32 s99, s99, 0
	v_and_b32_e32 v96, 0x7f, v240
	v_lshlrev_b32_e32 v96, 7, v96
	v_add_u32_e32 v96, s32, v96
	v_mov_b32_e32 v97, 0
	v_lshl_add_u64 v[96:97], s[98:99], 0, v[96:97]
	global_load_dword v98, v[96:97], off
	v_readlane_b32 s0, v254, 18
	s_add_i32 s16, s0, 4
	s_cmp_ge_i32 s16, s91
	s_cbranch_scc1 .LBB0_675
	v_readlane_b32 s2, v250, 55
	v_readlane_b32 s3, v250, 56
	s_mov_b64 s[0:1], -1
	s_and_b64 vcc, exec, s[2:3]
	s_cbranch_vccz .LBB0_659
	s_waitcnt vmcnt(1)
	v_readlane_b32 s0, v251, 12
	v_readlane_b32 s1, v251, 13
	s_andn2_b64 vcc, exec, s[0:1]
	s_waitcnt lgkmcnt(0)
	s_barrier
	s_cbranch_vccnz .LBB0_658
	v_mov_b32_e32 v0, v81
	s_nop 0
	v_mbcnt_lo_u32_b32 v0, -1, v0
	v_mbcnt_hi_u32_b32 v0, -1, v0
	v_cmp_eq_u32_e32 vcc, 0, v0
	s_and_saveexec_b64 s[0:1], vcc
	s_cbranch_execz .LBB0_657
	v_readlane_b32 s2, v250, 5
	s_waitcnt vmcnt(0) expcnt(0) lgkmcnt(0)
	s_nop 0
	v_mov_b32_e32 v0, s2
	ds_read_b32 v2, v0
	ds_read_b32 v0, v0 offset:4
	s_waitcnt lgkmcnt(1)
	v_cmp_ne_u32_e32 vcc, 0, v2
	s_cbranch_vccnz .LBB0_625
	v_readlane_b32 s4, v250, 0
	v_readlane_b32 s5, v250, 1
	s_load_dwordx2 s[2:3], s[4:5], 0x4
	s_mov_b32 s9, 1
	s_waitcnt lgkmcnt(0)
	s_mul_i32 s8, s2, s33
	s_mul_i32 s8, s8, s3
	s_branch .LBB0_610

.LBB0_677:
	s_andn2_b64 vcc, exec, s[0:1]
	s_cbranch_vccnz .LBB0_783
	v_mov_b32_e32 v0, v81
	s_and_b64 vcc, exec, s[80:81]
	v_mbcnt_lo_u32_b32 v0, -1, v0
	v_mbcnt_hi_u32_b32 v0, -1, v0
	v_add_u32_e32 v0, s69, v0
	s_nop 0
	v_readfirstlane_b32 s2, v0
	s_cbranch_vccnz .LBB0_714
	v_readlane_b32 s0, v254, 19
	v_readlane_b32 s1, v254, 20
	s_add_u32 s48, s0, 0x2600000
	s_addc_u32 s0, s1, 0
	s_ashr_i32 s4, s2, 6
	s_lshl_b32 s5, s4, 10
	s_add_i32 s31, s5, 0x100
	s_waitcnt lgkmcnt(0)
	v_lshlrev_b32_e32 v220, 4, v0
	s_and_b32 s49, s0, 0xffff
	s_mov_b32 s51, s59
	s_add_i32 s55, s31, 0x10000
	v_readlane_b32 s0, v253, 36
	s_mov_b32 m0, s55
	s_nop 0
	buffer_load_dwordx4 v220, s[48:51], s0 offen lds
	v_add_u32_e32 v221, 0x2000, v220
	s_add_i32 s76, s31, 0x12000
	s_mov_b32 m0, s76
	s_nop 0
	buffer_load_dwordx4 v221, s[48:51], s0 offen lds
	s_add_i32 s77, s31, 0x14000
	v_readlane_b32 s0, v253, 31
	s_mov_b32 m0, s77
	s_nop 0
	buffer_load_dwordx4 v220, s[48:51], s0 offen lds
	v_readlane_b32 s8, v254, 10
	s_add_i32 s78, s31, 0x16000
	s_mov_b32 m0, s78
	s_nop 0
	buffer_load_dwordx4 v221, s[48:51], s0 offen lds
	v_readlane_b32 s10, v254, 12
	v_readlane_b32 s11, v254, 13
	v_readlane_b32 s9, v254, 11
	s_mov_b32 s10, s26
	s_mov_b32 s11, s27
	v_readlane_b32 s0, v253, 34
	s_mov_b32 m0, s31
	s_nop 0
	buffer_load_dwordx4 v220, s[8:11], s0 offen lds
	s_add_i32 s79, s31, 0x2000
	s_mov_b32 m0, s79
	s_nop 0
	buffer_load_dwordx4 v221, s[8:11], s0 offen lds
	s_add_i32 s82, s31, 0x4000
	v_readlane_b32 s6, v253, 32
	s_mov_b32 m0, s82
	s_nop 0
	buffer_load_dwordx4 v220, s[8:11], s6 offen lds
	v_writelane_b32 v254, s8, 10
	s_ashr_i32 s3, s2, 8
	s_add_i32 s83, s31, 0x6000
	v_writelane_b32 v254, s9, 11
	s_mov_b32 m0, s83
	s_nop 0
	buffer_load_dwordx4 v221, s[8:11], s6 offen lds
	v_readlane_b32 s32, v253, 33
	v_readlane_b32 s98, v253, 35
	v_readlane_b32 s99, v253, 37
	s_nop 2
	s_add_i32 m0, s31, 0x18000
	s_nop 0
	buffer_load_dwordx4 v220, s[48:51], s32 offen lds
	s_add_i32 m0, s31, 0x1a000
	s_nop 0
	buffer_load_dwordx4 v221, s[48:51], s32 offen lds
	s_add_i32 m0, s31, 0x8000
	s_nop 0
	buffer_load_dwordx4 v220, s[8:11], s98 offen lds
	s_add_i32 m0, s31, 0xa000
	s_nop 0
	buffer_load_dwordx4 v221, s[8:11], s98 offen lds
	s_add_i32 m0, s31, 0x1c000
	s_nop 0
	buffer_load_dwordx4 v220, s[48:51], s99 offen lds
	s_add_i32 m0, s31, 0x1e000
	s_nop 0
	buffer_load_dwordx4 v221, s[48:51], s99 offen lds
	s_cmp_eq_u32 s3, 1
	v_writelane_b32 v254, s10, 12
	s_cselect_b64 s[0:1], -1, 0
	s_cmp_lg_u32 s3, 1
	v_writelane_b32 v254, s11, 13
	s_cbranch_scc1 .LBB0_681
	s_nop 0

.Lpeel_p4:
	s_waitcnt lgkmcnt(0)
	v_add_u32_e32 v156, 0x10000, v222
	v_add_u32_e32 v180, 0x14000, v222
	ds_read_b128 v[128:131], v156
	ds_read_b128 v[140:143], v156 offset:1024
	ds_read_b128 v[152:155], v156 offset:2048
	ds_read_b128 v[156:159], v156 offset:3072
	ds_read_b128 v[168:171], v180
	ds_read_b128 v[172:175], v180 offset:1024
	ds_read_b128 v[176:179], v180 offset:2048
	ds_read_b128 v[180:183], v180 offset:3072
	s_add_i32 s11, s8, 0xfff84000
	s_cmp_eq_u32 s10, 28
	s_cselect_b32 s13, s6, s11
	s_cselect_b32 s12, s7, s9
	s_or_b32 s11, s13, 0x4000
	ds_read_b128 v[184:187], v223
	ds_read_b128 v[188:191], v223 offset:1024
	ds_read_b128 v[192:195], v223 offset:2048
	ds_read_b128 v[196:199], v223 offset:3072
	ds_read_b128 v[200:203], v223 offset:4096
	ds_read_b128 v[204:207], v223 offset:5120
	ds_read_b128 v[224:227], v223 offset:6144
	ds_read_b128 v[228:231], v223 offset:7168
	s_mov_b32 m0, s89
	s_nop 0
	buffer_load_dwordx4 v220, s[64:67], s8 offen lds
	s_nop 0
	s_mov_b32 m0, s91
	s_nop 0
	buffer_load_dwordx4 v221, s[64:67], s8 offen lds
	s_waitcnt vmcnt(24)
	s_waitcnt lgkmcnt(0)
	s_cmp_lg_u32 s101, 0
	s_cbranch_scc1 .Lhbp_p4_0
	s_barrier
.Lhbp_p4_0:
	s_setprio 1
	s_waitcnt lgkmcnt(7)
	v_mfma_f32_16x16x32_bf16 v[164:167], v[128:131], v[184:187], 0
	v_mfma_f32_16x16x32_bf16 v[160:163], v[152:155], v[184:187], 0
	s_waitcnt lgkmcnt(5)
	v_mfma_f32_16x16x32_bf16 v[136:139], v[128:131], v[192:195], 0
	v_mfma_f32_16x16x32_bf16 v[132:135], v[152:155], v[192:195], 0
	s_waitcnt lgkmcnt(3)
	v_mfma_f32_16x16x32_bf16 v[116:119], v[128:131], v[200:203], 0
	v_mfma_f32_16x16x32_bf16 v[112:115], v[152:155], v[200:203], 0
	s_waitcnt lgkmcnt(1)
	v_mfma_f32_16x16x32_bf16 v[76:79], v[128:131], v[224:227], 0
	v_mfma_f32_16x16x32_bf16 v[72:75], v[152:155], v[224:227], 0
	v_mfma_f32_16x16x32_bf16 v[164:167], v[140:143], v[188:191], v[164:167]
	v_mfma_f32_16x16x32_bf16 v[160:163], v[156:159], v[188:191], v[160:163]
	v_mfma_f32_16x16x32_bf16 v[136:139], v[140:143], v[196:199], v[136:139]
	v_mfma_f32_16x16x32_bf16 v[132:135], v[156:159], v[196:199], v[132:135]
	v_mfma_f32_16x16x32_bf16 v[116:119], v[140:143], v[204:207], v[116:119]
	v_mfma_f32_16x16x32_bf16 v[112:115], v[156:159], v[204:207], v[112:115]
	s_waitcnt lgkmcnt(0)
	v_mfma_f32_16x16x32_bf16 v[76:79], v[140:143], v[228:231], v[76:79]
	v_mfma_f32_16x16x32_bf16 v[72:75], v[156:159], v[228:231], v[72:75]
	s_setprio 0
	s_setprio 1
	v_mfma_f32_16x16x32_bf16 v[148:151], v[168:171], v[184:187], 0
	v_mfma_f32_16x16x32_bf16 v[144:147], v[176:179], v[184:187], 0
	v_mfma_f32_16x16x32_bf16 v[124:127], v[168:171], v[192:195], 0
	v_mfma_f32_16x16x32_bf16 v[120:123], v[176:179], v[192:195], 0
	v_mfma_f32_16x16x32_bf16 v[108:111], v[168:171], v[200:203], 0
	v_mfma_f32_16x16x32_bf16 v[104:107], v[176:179], v[200:203], 0
	v_mfma_f32_16x16x32_bf16 v[68:71], v[168:171], v[224:227], 0
	v_mfma_f32_16x16x32_bf16 v[64:67], v[176:179], v[224:227], 0
	v_mfma_f32_16x16x32_bf16 v[148:151], v[172:175], v[188:191], v[148:151]
	v_mfma_f32_16x16x32_bf16 v[144:147], v[180:183], v[188:191], v[144:147]
	v_mfma_f32_16x16x32_bf16 v[124:127], v[172:175], v[196:199], v[124:127]
	v_mfma_f32_16x16x32_bf16 v[120:123], v[180:183], v[196:199], v[120:123]
	v_mfma_f32_16x16x32_bf16 v[108:111], v[172:175], v[204:207], v[108:111]
	v_mfma_f32_16x16x32_bf16 v[104:107], v[180:183], v[204:207], v[104:107]
	v_mfma_f32_16x16x32_bf16 v[68:71], v[172:175], v[228:231], v[68:71]
	v_mfma_f32_16x16x32_bf16 v[64:67], v[180:183], v[228:231], v[64:67]
	s_setprio 0
	s_cmp_eq_u32 s101, 0
	s_cbranch_scc1 .Lhbp_p4_1
	s_barrier
.Lhbp_p4_1:
	ds_read_b128 v[184:187], v223 offset:16384
	ds_read_b128 v[188:191], v223 offset:17408
	ds_read_b128 v[192:195], v223 offset:18432
	ds_read_b128 v[196:199], v223 offset:19456
	ds_read_b128 v[200:203], v223 offset:20480
	ds_read_b128 v[204:207], v223 offset:21504
	ds_read_b128 v[224:227], v223 offset:22528
	ds_read_b128 v[228:231], v223 offset:23552
	s_mov_b32 m0, s55
	s_nop 0
	buffer_load_dwordx4 v220, s[48:51], s12 offen lds
	s_add_i32 s14, s12, 0x80000
	s_mov_b32 m0, s76
	s_nop 0
	buffer_load_dwordx4 v221, s[48:51], s12 offen lds
	s_nop 0
	s_mov_b32 m0, s77
	s_nop 0
	buffer_load_dwordx4 v220, s[48:51], s14 offen lds
	s_nop 0
	s_mov_b32 m0, s78
	s_nop 0
	buffer_load_dwordx4 v221, s[48:51], s14 offen lds
	s_nop 0
	s_mov_b32 m0, s31
	s_nop 0
	buffer_load_dwordx4 v220, s[64:67], s13 offen lds
	s_nop 0
	s_mov_b32 m0, s79
	s_nop 0
	buffer_load_dwordx4 v221, s[64:67], s13 offen lds
	s_waitcnt vmcnt(24)
	s_waitcnt lgkmcnt(0)
	s_cmp_lg_u32 s101, 0
	s_cbranch_scc1 .Lhbp_p4_2
	s_barrier
.Lhbp_p4_2:
	s_setprio 1
	s_waitcnt lgkmcnt(7)
	v_mfma_f32_16x16x32_bf16 v[60:63], v[128:131], v[184:187], 0
	v_mfma_f32_16x16x32_bf16 v[56:59], v[152:155], v[184:187], 0
	s_waitcnt lgkmcnt(5)
	v_mfma_f32_16x16x32_bf16 v[44:47], v[128:131], v[192:195], 0
	v_mfma_f32_16x16x32_bf16 v[40:43], v[152:155], v[192:195], 0
	s_waitcnt lgkmcnt(3)
	v_mfma_f32_16x16x32_bf16 v[28:31], v[128:131], v[200:203], 0
	v_mfma_f32_16x16x32_bf16 v[24:27], v[152:155], v[200:203], 0
	s_waitcnt lgkmcnt(1)
	v_mfma_f32_16x16x32_bf16 v[12:15], v[128:131], v[224:227], 0
	v_mfma_f32_16x16x32_bf16 v[8:11], v[152:155], v[224:227], 0
	v_mfma_f32_16x16x32_bf16 v[60:63], v[140:143], v[188:191], v[60:63]
	v_mfma_f32_16x16x32_bf16 v[56:59], v[156:159], v[188:191], v[56:59]
	v_mfma_f32_16x16x32_bf16 v[44:47], v[140:143], v[196:199], v[44:47]
	v_mfma_f32_16x16x32_bf16 v[40:43], v[156:159], v[196:199], v[40:43]
	v_mfma_f32_16x16x32_bf16 v[28:31], v[140:143], v[204:207], v[28:31]
	v_mfma_f32_16x16x32_bf16 v[24:27], v[156:159], v[204:207], v[24:27]
	s_waitcnt lgkmcnt(0)
	v_mfma_f32_16x16x32_bf16 v[12:15], v[140:143], v[228:231], v[12:15]
	v_mfma_f32_16x16x32_bf16 v[8:11], v[156:159], v[228:231], v[8:11]
	s_setprio 0
	s_setprio 1
	v_mfma_f32_16x16x32_bf16 v[52:55], v[168:171], v[184:187], 0
	v_mfma_f32_16x16x32_bf16 v[48:51], v[176:179], v[184:187], 0
	v_mfma_f32_16x16x32_bf16 v[36:39], v[168:171], v[192:195], 0
	v_mfma_f32_16x16x32_bf16 v[32:35], v[176:179], v[192:195], 0
	v_mfma_f32_16x16x32_bf16 v[20:23], v[168:171], v[200:203], 0
	v_mfma_f32_16x16x32_bf16 v[16:19], v[176:179], v[200:203], 0
	v_mfma_f32_16x16x32_bf16 v[4:7], v[168:171], v[224:227], 0
	v_mfma_f32_16x16x32_bf16 v[0:3], v[176:179], v[224:227], 0
	v_mfma_f32_16x16x32_bf16 v[52:55], v[172:175], v[188:191], v[52:55]
	v_mfma_f32_16x16x32_bf16 v[48:51], v[180:183], v[188:191], v[48:51]
	v_mfma_f32_16x16x32_bf16 v[36:39], v[172:175], v[196:199], v[36:39]
	v_mfma_f32_16x16x32_bf16 v[32:35], v[180:183], v[196:199], v[32:35]
	v_mfma_f32_16x16x32_bf16 v[20:23], v[172:175], v[204:207], v[20:23]
	v_mfma_f32_16x16x32_bf16 v[16:19], v[180:183], v[204:207], v[16:19]
	v_mfma_f32_16x16x32_bf16 v[4:7], v[172:175], v[228:231], v[4:7]
	v_mfma_f32_16x16x32_bf16 v[0:3], v[180:183], v[228:231], v[0:3]
	s_setprio 0
	s_cmp_eq_u32 s101, 0
	s_cbranch_scc1 .Lhbp_p4_3
	s_barrier
.Lhbp_p4_3:
	v_add_u32_e32 v156, 0x18000, v222
	v_add_u32_e32 v180, 0x1c000, v222
	ds_read_b128 v[128:131], v156
	ds_read_b128 v[140:143], v156 offset:1024
	ds_read_b128 v[152:155], v156 offset:2048
	ds_read_b128 v[156:159], v156 offset:3072
	ds_read_b128 v[168:171], v180
	ds_read_b128 v[172:175], v180 offset:1024
	ds_read_b128 v[176:179], v180 offset:2048
	ds_read_b128 v[180:183], v180 offset:3072
	ds_read_b128 v[184:187], v223 offset:32768
	ds_read_b128 v[188:191], v223 offset:33792
	ds_read_b128 v[192:195], v223 offset:34816
	ds_read_b128 v[196:199], v223 offset:35840
	ds_read_b128 v[200:203], v223 offset:36864
	ds_read_b128 v[204:207], v223 offset:37888
	ds_read_b128 v[224:227], v223 offset:38912
	ds_read_b128 v[228:231], v223 offset:39936
	s_add_i32 s13, s13, 0x80000
	s_mov_b32 m0, s82
	s_nop 0
	buffer_load_dwordx4 v220, s[64:67], s13 offen lds
	s_nop 0
	s_mov_b32 m0, s83
	s_nop 0
	buffer_load_dwordx4 v221, s[64:67], s13 offen lds
	s_waitcnt vmcnt(8)
	s_waitcnt lgkmcnt(0)
	s_cmp_lg_u32 s101, 0
	s_cbranch_scc1 .Lhbp_p4_4
	s_barrier
.Lhbp_p4_4:
	s_setprio 1
	s_waitcnt lgkmcnt(7)
	v_mfma_f32_16x16x32_bf16 v[164:167], v[128:131], v[184:187], v[164:167]
	v_mfma_f32_16x16x32_bf16 v[160:163], v[152:155], v[184:187], v[160:163]
	s_waitcnt lgkmcnt(5)
	v_mfma_f32_16x16x32_bf16 v[136:139], v[128:131], v[192:195], v[136:139]
	v_mfma_f32_16x16x32_bf16 v[132:135], v[152:155], v[192:195], v[132:135]
	s_waitcnt lgkmcnt(3)
	v_mfma_f32_16x16x32_bf16 v[116:119], v[128:131], v[200:203], v[116:119]
	v_mfma_f32_16x16x32_bf16 v[112:115], v[152:155], v[200:203], v[112:115]
	s_waitcnt lgkmcnt(1)
	v_mfma_f32_16x16x32_bf16 v[76:79], v[128:131], v[224:227], v[76:79]
	v_mfma_f32_16x16x32_bf16 v[72:75], v[152:155], v[224:227], v[72:75]
	v_mfma_f32_16x16x32_bf16 v[164:167], v[140:143], v[188:191], v[164:167]
	v_mfma_f32_16x16x32_bf16 v[160:163], v[156:159], v[188:191], v[160:163]
	v_mfma_f32_16x16x32_bf16 v[136:139], v[140:143], v[196:199], v[136:139]
	v_mfma_f32_16x16x32_bf16 v[132:135], v[156:159], v[196:199], v[132:135]
	v_mfma_f32_16x16x32_bf16 v[116:119], v[140:143], v[204:207], v[116:119]
	v_mfma_f32_16x16x32_bf16 v[112:115], v[156:159], v[204:207], v[112:115]
	s_waitcnt lgkmcnt(0)
	v_mfma_f32_16x16x32_bf16 v[76:79], v[140:143], v[228:231], v[76:79]
	v_mfma_f32_16x16x32_bf16 v[72:75], v[156:159], v[228:231], v[72:75]
	s_setprio 0
	s_setprio 1
	v_mfma_f32_16x16x32_bf16 v[148:151], v[168:171], v[184:187], v[148:151]
	v_mfma_f32_16x16x32_bf16 v[144:147], v[176:179], v[184:187], v[144:147]
	v_mfma_f32_16x16x32_bf16 v[124:127], v[168:171], v[192:195], v[124:127]
	v_mfma_f32_16x16x32_bf16 v[120:123], v[176:179], v[192:195], v[120:123]
	v_mfma_f32_16x16x32_bf16 v[108:111], v[168:171], v[200:203], v[108:111]
	v_mfma_f32_16x16x32_bf16 v[104:107], v[176:179], v[200:203], v[104:107]
	v_mfma_f32_16x16x32_bf16 v[68:71], v[168:171], v[224:227], v[68:71]
	v_mfma_f32_16x16x32_bf16 v[64:67], v[176:179], v[224:227], v[64:67]
	v_mfma_f32_16x16x32_bf16 v[148:151], v[172:175], v[188:191], v[148:151]
	v_mfma_f32_16x16x32_bf16 v[144:147], v[180:183], v[188:191], v[144:147]
	v_mfma_f32_16x16x32_bf16 v[124:127], v[172:175], v[196:199], v[124:127]
	v_mfma_f32_16x16x32_bf16 v[120:123], v[180:183], v[196:199], v[120:123]
	v_mfma_f32_16x16x32_bf16 v[108:111], v[172:175], v[204:207], v[108:111]
	v_mfma_f32_16x16x32_bf16 v[104:107], v[180:183], v[204:207], v[104:107]
	v_mfma_f32_16x16x32_bf16 v[68:71], v[172:175], v[228:231], v[68:71]
	v_mfma_f32_16x16x32_bf16 v[64:67], v[180:183], v[228:231], v[64:67]
	s_setprio 0
	s_cmp_eq_u32 s101, 0
	s_cbranch_scc1 .Lhbp_p4_5
	s_barrier
.Lhbp_p4_5:
	ds_read_b128 v[184:187], v223 offset:49152
	ds_read_b128 v[188:191], v223 offset:50176
	ds_read_b128 v[192:195], v223 offset:51200
	ds_read_b128 v[196:199], v223 offset:52224
	ds_read_b128 v[200:203], v223 offset:53248
	ds_read_b128 v[204:207], v223 offset:54272
	ds_read_b128 v[224:227], v223 offset:55296
	ds_read_b128 v[228:231], v223 offset:56320
	s_or_b32 s13, s12, 0x4000
	s_mov_b32 m0, s34
	s_nop 0
	buffer_load_dwordx4 v220, s[48:51], s13 offen lds
	s_add_i32 s12, s12, 0x84000
	s_mov_b32 m0, s84
	s_nop 0
	buffer_load_dwordx4 v221, s[48:51], s13 offen lds
	s_nop 0
	s_mov_b32 m0, s87
	s_nop 0
	buffer_load_dwordx4 v220, s[48:51], s12 offen lds
	s_nop 0
	s_mov_b32 m0, s88
	s_nop 0
	buffer_load_dwordx4 v221, s[48:51], s12 offen lds
	s_nop 0
	s_mov_b32 m0, s85
	s_nop 0
	buffer_load_dwordx4 v220, s[64:67], s11 offen lds
	s_nop 0
	s_mov_b32 m0, s86
	s_nop 0
	buffer_load_dwordx4 v221, s[64:67], s11 offen lds
	s_waitcnt vmcnt(8)
	s_waitcnt lgkmcnt(0)
	s_cmp_lg_u32 s101, 0
	s_cbranch_scc1 .Lhbp_p4_6
	s_barrier
.Lhbp_p4_6:
	s_setprio 1
	s_waitcnt lgkmcnt(7)
	v_mfma_f32_16x16x32_bf16 v[60:63], v[128:131], v[184:187], v[60:63]
	v_mfma_f32_16x16x32_bf16 v[56:59], v[152:155], v[184:187], v[56:59]
	s_waitcnt lgkmcnt(5)
	v_mfma_f32_16x16x32_bf16 v[44:47], v[128:131], v[192:195], v[44:47]
	v_mfma_f32_16x16x32_bf16 v[40:43], v[152:155], v[192:195], v[40:43]
	s_waitcnt lgkmcnt(3)
	v_mfma_f32_16x16x32_bf16 v[28:31], v[128:131], v[200:203], v[28:31]
	v_mfma_f32_16x16x32_bf16 v[24:27], v[152:155], v[200:203], v[24:27]
	s_waitcnt lgkmcnt(1)
	v_mfma_f32_16x16x32_bf16 v[12:15], v[128:131], v[224:227], v[12:15]
	v_mfma_f32_16x16x32_bf16 v[8:11], v[152:155], v[224:227], v[8:11]
	v_mfma_f32_16x16x32_bf16 v[60:63], v[140:143], v[188:191], v[60:63]
	v_mfma_f32_16x16x32_bf16 v[56:59], v[156:159], v[188:191], v[56:59]
	v_mfma_f32_16x16x32_bf16 v[44:47], v[140:143], v[196:199], v[44:47]
	v_mfma_f32_16x16x32_bf16 v[40:43], v[156:159], v[196:199], v[40:43]
	v_mfma_f32_16x16x32_bf16 v[28:31], v[140:143], v[204:207], v[28:31]
	v_mfma_f32_16x16x32_bf16 v[24:27], v[156:159], v[204:207], v[24:27]
	s_waitcnt lgkmcnt(0)
	v_mfma_f32_16x16x32_bf16 v[12:15], v[140:143], v[228:231], v[12:15]
	v_mfma_f32_16x16x32_bf16 v[8:11], v[156:159], v[228:231], v[8:11]
	s_setprio 0
	s_setprio 1
	v_mfma_f32_16x16x32_bf16 v[52:55], v[168:171], v[184:187], v[52:55]
	v_mfma_f32_16x16x32_bf16 v[48:51], v[176:179], v[184:187], v[48:51]
	v_mfma_f32_16x16x32_bf16 v[36:39], v[168:171], v[192:195], v[36:39]
	v_mfma_f32_16x16x32_bf16 v[32:35], v[176:179], v[192:195], v[32:35]
	v_mfma_f32_16x16x32_bf16 v[20:23], v[168:171], v[200:203], v[20:23]
	v_mfma_f32_16x16x32_bf16 v[16:19], v[176:179], v[200:203], v[16:19]
	v_mfma_f32_16x16x32_bf16 v[4:7], v[168:171], v[224:227], v[4:7]
	v_mfma_f32_16x16x32_bf16 v[0:3], v[176:179], v[224:227], v[0:3]
	v_mfma_f32_16x16x32_bf16 v[52:55], v[172:175], v[188:191], v[52:55]
	v_mfma_f32_16x16x32_bf16 v[48:51], v[180:183], v[188:191], v[48:51]
	v_mfma_f32_16x16x32_bf16 v[36:39], v[172:175], v[196:199], v[36:39]
	v_mfma_f32_16x16x32_bf16 v[32:35], v[180:183], v[196:199], v[32:35]
	v_mfma_f32_16x16x32_bf16 v[20:23], v[172:175], v[204:207], v[20:23]
	v_mfma_f32_16x16x32_bf16 v[16:19], v[180:183], v[204:207], v[16:19]
	v_mfma_f32_16x16x32_bf16 v[4:7], v[172:175], v[228:231], v[4:7]
	v_mfma_f32_16x16x32_bf16 v[0:3], v[180:183], v[228:231], v[0:3]
	s_setprio 0
	s_cmp_eq_u32 s101, 0
	s_cbranch_scc1 .Lhbp_p4_7
	s_barrier
.Lhbp_p4_7:
	s_add_i32 s10, s10, 2
	s_add_i32 s8, s8, 0x8000
	s_add_i32 s9, s9, 0x8000
.LBB0_691:
	v_add_u32_e32 v156, 0x10000, v222
	v_add_u32_e32 v180, 0x14000, v222
	ds_read_b128 v[128:131], v156
	ds_read_b128 v[140:143], v156 offset:1024
	ds_read_b128 v[152:155], v156 offset:2048
	ds_read_b128 v[156:159], v156 offset:3072
	ds_read_b128 v[168:171], v180
	ds_read_b128 v[172:175], v180 offset:1024
	ds_read_b128 v[176:179], v180 offset:2048
	ds_read_b128 v[180:183], v180 offset:3072
	s_add_i32 s11, s8, 0xfff84000
	s_cmp_eq_u32 s10, 28
	s_cselect_b32 s13, s6, s11
	s_cselect_b32 s12, s7, s9
	s_or_b32 s11, s13, 0x4000
	ds_read_b128 v[184:187], v223
	ds_read_b128 v[188:191], v223 offset:1024
	ds_read_b128 v[192:195], v223 offset:2048
	ds_read_b128 v[196:199], v223 offset:3072
	ds_read_b128 v[200:203], v223 offset:4096
	ds_read_b128 v[204:207], v223 offset:5120
	ds_read_b128 v[224:227], v223 offset:6144
	ds_read_b128 v[228:231], v223 offset:7168
	s_mov_b32 m0, s89
	s_nop 0
	buffer_load_dwordx4 v220, s[64:67], s8 offen lds
	s_nop 0
	s_mov_b32 m0, s91
	s_nop 0
	buffer_load_dwordx4 v221, s[64:67], s8 offen lds
	s_waitcnt vmcnt(8)
	s_waitcnt lgkmcnt(0)
	s_cmp_lg_u32 s101, 0
	s_cbranch_scc1 .Lhb_p4_0
	s_barrier

.Lhb_p4_1:
	ds_read_b128 v[184:187], v223 offset:16384
	ds_read_b128 v[188:191], v223 offset:17408
	ds_read_b128 v[192:195], v223 offset:18432
	ds_read_b128 v[196:199], v223 offset:19456
	ds_read_b128 v[200:203], v223 offset:20480
	ds_read_b128 v[204:207], v223 offset:21504
	ds_read_b128 v[224:227], v223 offset:22528
	ds_read_b128 v[228:231], v223 offset:23552
	s_mov_b32 m0, s55
	s_nop 0
	buffer_load_dwordx4 v220, s[48:51], s12 offen lds
	s_add_i32 s14, s12, 0x80000
	s_mov_b32 m0, s76
	s_nop 0
	buffer_load_dwordx4 v221, s[48:51], s12 offen lds
	s_nop 0
	s_mov_b32 m0, s77
	s_nop 0
	buffer_load_dwordx4 v220, s[48:51], s14 offen lds
	s_nop 0
	s_mov_b32 m0, s78
	s_nop 0
	buffer_load_dwordx4 v221, s[48:51], s14 offen lds
	s_nop 0
	s_mov_b32 m0, s31
	s_nop 0
	buffer_load_dwordx4 v220, s[64:67], s13 offen lds
	s_nop 0
	s_mov_b32 m0, s79
	s_nop 0
	buffer_load_dwordx4 v221, s[64:67], s13 offen lds
	s_waitcnt vmcnt(8)
	s_waitcnt lgkmcnt(0)
	s_cmp_lg_u32 s101, 0
	s_cbranch_scc1 .Lhb_p4_2
	s_barrier

.Lhb_p4_7:
	s_add_i32 s10, s10, 2
	s_add_i32 s8, s8, 0x8000
	s_add_i32 s9, s9, 0x8000
	s_cmp_gt_u32 s10, 29
	s_cbranch_scc0 .LBB0_691
	s_and_b64 vcc, exec, s[2:3]
	s_cbranch_vccz .LBB0_694
	s_nop 0

.LBB0_710:
	s_or_b64 exec, exec, s[4:5]
	s_andn2_b64 vcc, exec, s[40:41]
	s_mov_b64 s[4:5], -1
	s_cbranch_vccnz .LBB0_683
	s_andn2_b64 vcc, exec, s[0:1]
	s_cbranch_vccnz .LBB0_682
	s_nop 0
	s_branch .LBB0_682

.LBB0_714:
	v_readfirstlane_b32 s100, v240
	v_readlane_b32 s98, v254, 19
	v_readlane_b32 s99, v254, 20
	v_readlane_b32 s32, v253, 20
	v_readlane_b32 vcc_lo, v253, 14
	s_lshr_b32 s100, s100, 7
	s_cmp_eq_u32 s100, 1
	s_cselect_b32 s32, vcc_lo, s32
	v_readlane_b32 vcc_lo, v253, 17
	s_cmp_eq_u32 s100, 2
	s_cselect_b32 s32, vcc_lo, s32
	v_readlane_b32 vcc_lo, v253, 21
	s_cmp_eq_u32 s100, 3
	s_cselect_b32 s32, vcc_lo, s32
	s_add_u32 s98, s98, 0x2e00000
	s_addc_u32 s99, s99, 0
	v_and_b32_e32 v96, 0x7f, v240
	v_lshlrev_b32_e32 v96, 7, v96
	v_add_u32_e32 v96, s32, v96
	v_mov_b32_e32 v97, 0
	v_lshl_add_u64 v[96:97], s[98:99], 0, v[96:97]
	global_load_dword v98, v[96:97], off
	v_readlane_b32 s0, v254, 18
	s_add_i32 s16, s0, 5
	s_cmp_ge_i32 s16, s91
	s_cbranch_scc1 .LBB0_783
	v_readlane_b32 s2, v250, 55
	v_readlane_b32 s3, v250, 56
	s_mov_b64 s[0:1], -1
	s_and_b64 vcc, exec, s[2:3]
	s_cbranch_vccz .LBB0_767
	s_waitcnt vmcnt(1)
	v_readlane_b32 s0, v251, 12
	v_readlane_b32 s1, v251, 13
	s_andn2_b64 vcc, exec, s[0:1]
	s_waitcnt lgkmcnt(0)
	s_barrier
	s_cbranch_vccnz .LBB0_766
	v_mov_b32_e32 v0, v81
	s_nop 0
	v_mbcnt_lo_u32_b32 v0, -1, v0
	v_mbcnt_hi_u32_b32 v0, -1, v0
	v_cmp_eq_u32_e32 vcc, 0, v0
	s_and_saveexec_b64 s[0:1], vcc
	s_cbranch_execz .LBB0_765
	v_readlane_b32 s2, v250, 5
	s_waitcnt vmcnt(0) expcnt(0) lgkmcnt(0)
	s_nop 0
	v_mov_b32_e32 v0, s2
	ds_read_b32 v2, v0
	ds_read_b32 v0, v0 offset:4
	s_waitcnt lgkmcnt(1)
	v_cmp_ne_u32_e32 vcc, 0, v2
	s_cbranch_vccnz .LBB0_733
	v_readlane_b32 s4, v250, 0
	v_readlane_b32 s5, v250, 1
	s_load_dwordx2 s[2:3], s[4:5], 0x4
	s_mov_b32 s9, 1
	s_waitcnt lgkmcnt(0)
	s_mul_i32 s8, s2, s33
	s_mul_i32 s8, s8, s3
	s_branch .LBB0_721

.LBB0_785:
	s_andn2_b64 vcc, exec, s[0:1]
	s_cbranch_vccnz .LBB0_871
	v_mov_b32_e32 v0, v81
	v_readlane_b32 s0, v252, 50
	v_mbcnt_lo_u32_b32 v0, -1, v0
	v_mbcnt_hi_u32_b32 v0, -1, v0
	v_add_u32_e32 v0, s69, v0
	v_readlane_b32 s1, v252, 51
	s_andn2_b64 vcc, exec, s[0:1]
	v_readfirstlane_b32 s2, v0
	s_cbranch_vccnz .LBB0_802
	v_readlane_b32 s0, v254, 19
	v_readlane_b32 s1, v254, 20
	s_add_u32 s28, s0, 0x2e00000
	s_addc_u32 s0, s1, 0
	s_ashr_i32 s4, s2, 6
	s_lshl_b32 s33, s4, 10
	s_add_i32 s6, s33, 0x100
	v_lshlrev_b32_e32 v166, 4, v0
	s_and_b32 s29, s0, 0xffff
	s_mov_b32 s31, s59
	s_add_i32 s7, s6, 0x10000
	v_readlane_b32 s0, v253, 20
	s_mov_b32 m0, s7
	s_nop 0
	buffer_load_dwordx4 v166, s[28:31], s0 offen lds
	v_add_u32_e32 v167, 0x2000, v166
	s_add_i32 s8, s6, 0x12000
	s_mov_b32 m0, s8
	s_nop 0
	buffer_load_dwordx4 v167, s[28:31], s0 offen lds
	s_add_i32 s9, s6, 0x14000
	v_readlane_b32 s0, v253, 14
	s_mov_b32 m0, s9
	s_nop 0
	buffer_load_dwordx4 v166, s[28:31], s0 offen lds
	s_add_i32 s10, s6, 0x16000
	s_mov_b32 m0, s10
	s_nop 0
	buffer_load_dwordx4 v167, s[28:31], s0 offen lds
	v_readlane_b32 s0, v253, 18
	s_mov_b32 m0, s6
	s_nop 0
	buffer_load_dwordx4 v166, s[24:27], s0 offen lds
	s_add_i32 s11, s6, 0x2000
	s_mov_b32 m0, s11
	s_nop 0
	buffer_load_dwordx4 v167, s[24:27], s0 offen lds
	s_add_i32 s12, s6, 0x4000
	v_readlane_b32 s3, v253, 16
	s_mov_b32 m0, s12
	s_nop 0
	buffer_load_dwordx4 v166, s[24:27], s3 offen lds
	s_ashr_i32 s5, s2, 8
	s_add_i32 s13, s6, 0x6000
	s_mov_b32 m0, s13
	s_nop 0
	buffer_load_dwordx4 v167, s[24:27], s3 offen lds
	v_readlane_b32 s32, v253, 17
	v_readlane_b32 s98, v253, 19
	v_readlane_b32 s99, v253, 21
	s_nop 2
	s_add_i32 m0, s6, 0x18000
	s_nop 0
	buffer_load_dwordx4 v166, s[28:31], s32 offen lds
	s_add_i32 m0, s6, 0x1a000
	s_nop 0
	buffer_load_dwordx4 v167, s[28:31], s32 offen lds
	s_add_i32 m0, s6, 0x8000
	s_nop 0
	buffer_load_dwordx4 v166, s[24:27], s98 offen lds
	s_add_i32 m0, s6, 0xa000
	s_nop 0
	buffer_load_dwordx4 v167, s[24:27], s98 offen lds
	s_add_i32 m0, s6, 0x1c000
	s_nop 0
	buffer_load_dwordx4 v166, s[28:31], s99 offen lds
	s_add_i32 m0, s6, 0x1e000
	s_nop 0
	buffer_load_dwordx4 v167, s[28:31], s99 offen lds
	s_cmp_eq_u32 s5, 1
	s_cselect_b64 s[0:1], -1, 0
	s_cmp_lg_u32 s5, 1
	s_cbranch_scc1 .LBB0_789
	s_nop 0

.Lpeel_p5:
	s_waitcnt lgkmcnt(0)
	v_add_u32_e32 v164, 0x10000, v168
	ds_read_b128 v[152:155], v164
	ds_read_b128 v[156:159], v164 offset:1024
	ds_read_b128 v[160:163], v164 offset:2048
	ds_read_b128 v[170:173], v164 offset:3072
	v_add_u32_e32 v164, 0x14000, v168
	ds_read_b128 v[174:177], v164
	ds_read_b128 v[178:181], v164 offset:1024
	ds_read_b128 v[182:185], v164 offset:2048
	ds_read_b128 v[186:189], v164 offset:3072
	s_add_i32 s53, s37, 0xfff84000
	s_cmp_eq_u32 s52, 28
	s_cselect_b32 s56, s4, s53
	s_cselect_b32 s55, s5, s51
	s_or_b32 s53, s56, 0x4000
	ds_read_b128 v[190:193], v169
	ds_read_b128 v[194:197], v169 offset:1024
	ds_read_b128 v[198:201], v169 offset:2048
	ds_read_b128 v[202:205], v169 offset:3072
	ds_read_b128 v[220:223], v169 offset:4096
	ds_read_b128 v[224:227], v169 offset:5120
	ds_read_b128 v[228:231], v169 offset:6144
	ds_read_b128 v[240:243], v169 offset:7168
	s_mov_b32 m0, s41
	s_nop 0
	buffer_load_dwordx4 v166, s[24:27], s37 offen lds
	s_nop 0
	s_mov_b32 m0, s42
	s_nop 0
	buffer_load_dwordx4 v167, s[24:27], s37 offen lds
	s_waitcnt vmcnt(24)
	s_waitcnt lgkmcnt(0)
	s_cmp_lg_u32 s101, 0
	s_cbranch_scc1 .Lhbp_p5_0
	s_barrier
.Lhbp_p5_0:
	s_setprio 1
	s_waitcnt lgkmcnt(7)
	v_mfma_f32_16x16x32_bf16 v[148:151], v[152:155], v[190:193], 0
	v_mfma_f32_16x16x32_bf16 v[140:143], v[160:163], v[190:193], 0
	s_waitcnt lgkmcnt(5)
	v_mfma_f32_16x16x32_bf16 v[132:135], v[152:155], v[198:201], 0
	v_mfma_f32_16x16x32_bf16 v[124:127], v[160:163], v[198:201], 0
	s_waitcnt lgkmcnt(3)
	v_mfma_f32_16x16x32_bf16 v[116:119], v[152:155], v[220:223], 0
	v_mfma_f32_16x16x32_bf16 v[108:111], v[160:163], v[220:223], 0
	s_waitcnt lgkmcnt(1)
	v_mfma_f32_16x16x32_bf16 v[76:79], v[152:155], v[228:231], 0
	v_mfma_f32_16x16x32_bf16 v[68:71], v[160:163], v[228:231], 0
	v_mfma_f32_16x16x32_bf16 v[148:151], v[156:159], v[194:197], v[148:151]
	v_mfma_f32_16x16x32_bf16 v[140:143], v[170:173], v[194:197], v[140:143]
	v_mfma_f32_16x16x32_bf16 v[132:135], v[156:159], v[202:205], v[132:135]
	v_mfma_f32_16x16x32_bf16 v[124:127], v[170:173], v[202:205], v[124:127]
	v_mfma_f32_16x16x32_bf16 v[116:119], v[156:159], v[224:227], v[116:119]
	v_mfma_f32_16x16x32_bf16 v[108:111], v[170:173], v[224:227], v[108:111]
	s_waitcnt lgkmcnt(0)
	v_mfma_f32_16x16x32_bf16 v[76:79], v[156:159], v[240:243], v[76:79]
	v_mfma_f32_16x16x32_bf16 v[68:71], v[170:173], v[240:243], v[68:71]
	s_setprio 0
	s_setprio 1
	v_mfma_f32_16x16x32_bf16 v[144:147], v[174:177], v[190:193], 0
	v_mfma_f32_16x16x32_bf16 v[136:139], v[182:185], v[190:193], 0
	v_mfma_f32_16x16x32_bf16 v[128:131], v[174:177], v[198:201], 0
	v_mfma_f32_16x16x32_bf16 v[120:123], v[182:185], v[198:201], 0
	v_mfma_f32_16x16x32_bf16 v[112:115], v[174:177], v[220:223], 0
	v_mfma_f32_16x16x32_bf16 v[104:107], v[182:185], v[220:223], 0
	v_mfma_f32_16x16x32_bf16 v[72:75], v[174:177], v[228:231], 0
	v_mfma_f32_16x16x32_bf16 v[64:67], v[182:185], v[228:231], 0
	v_mfma_f32_16x16x32_bf16 v[144:147], v[178:181], v[194:197], v[144:147]
	v_mfma_f32_16x16x32_bf16 v[136:139], v[186:189], v[194:197], v[136:139]
	v_mfma_f32_16x16x32_bf16 v[128:131], v[178:181], v[202:205], v[128:131]
	v_mfma_f32_16x16x32_bf16 v[120:123], v[186:189], v[202:205], v[120:123]
	v_mfma_f32_16x16x32_bf16 v[112:115], v[178:181], v[224:227], v[112:115]
	v_mfma_f32_16x16x32_bf16 v[104:107], v[186:189], v[224:227], v[104:107]
	v_mfma_f32_16x16x32_bf16 v[72:75], v[178:181], v[240:243], v[72:75]
	v_mfma_f32_16x16x32_bf16 v[64:67], v[186:189], v[240:243], v[64:67]
	s_setprio 0
	s_cmp_eq_u32 s101, 0
	s_cbranch_scc1 .Lhbp_p5_1
	s_barrier
.Lhbp_p5_1:
	ds_read_b128 v[190:193], v169 offset:16384
	ds_read_b128 v[194:197], v169 offset:17408
	ds_read_b128 v[198:201], v169 offset:18432
	ds_read_b128 v[202:205], v169 offset:19456
	ds_read_b128 v[220:223], v169 offset:20480
	ds_read_b128 v[224:227], v169 offset:21504
	ds_read_b128 v[228:231], v169 offset:22528
	ds_read_b128 v[240:243], v169 offset:23552
	s_mov_b32 m0, s7
	s_nop 0
	buffer_load_dwordx4 v166, s[28:31], s55 offen lds
	s_add_i32 s57, s55, 0x80000
	s_mov_b32 m0, s8
	s_nop 0
	buffer_load_dwordx4 v167, s[28:31], s55 offen lds
	s_nop 0
	s_mov_b32 m0, s9
	s_nop 0
	buffer_load_dwordx4 v166, s[28:31], s57 offen lds
	s_nop 0
	s_mov_b32 m0, s10
	s_nop 0
	buffer_load_dwordx4 v167, s[28:31], s57 offen lds
	s_nop 0
	s_mov_b32 m0, s6
	s_nop 0
	buffer_load_dwordx4 v166, s[24:27], s56 offen lds
	s_nop 0
	s_mov_b32 m0, s11
	s_nop 0
	buffer_load_dwordx4 v167, s[24:27], s56 offen lds
	s_waitcnt vmcnt(24)
	s_waitcnt lgkmcnt(0)
	s_cmp_lg_u32 s101, 0
	s_cbranch_scc1 .Lhbp_p5_2
	s_barrier
.Lhbp_p5_2:
	s_setprio 1
	s_waitcnt lgkmcnt(7)
	v_mfma_f32_16x16x32_bf16 v[60:63], v[152:155], v[190:193], 0
	v_mfma_f32_16x16x32_bf16 v[52:55], v[160:163], v[190:193], 0
	s_waitcnt lgkmcnt(5)
	v_mfma_f32_16x16x32_bf16 v[44:47], v[152:155], v[198:201], 0
	v_mfma_f32_16x16x32_bf16 v[36:39], v[160:163], v[198:201], 0
	s_waitcnt lgkmcnt(3)
	v_mfma_f32_16x16x32_bf16 v[28:31], v[152:155], v[220:223], 0
	v_mfma_f32_16x16x32_bf16 v[20:23], v[160:163], v[220:223], 0
	s_waitcnt lgkmcnt(1)
	v_mfma_f32_16x16x32_bf16 v[12:15], v[152:155], v[228:231], 0
	v_mfma_f32_16x16x32_bf16 v[4:7], v[160:163], v[228:231], 0
	v_mfma_f32_16x16x32_bf16 v[60:63], v[156:159], v[194:197], v[60:63]
	v_mfma_f32_16x16x32_bf16 v[52:55], v[170:173], v[194:197], v[52:55]
	v_mfma_f32_16x16x32_bf16 v[44:47], v[156:159], v[202:205], v[44:47]
	v_mfma_f32_16x16x32_bf16 v[36:39], v[170:173], v[202:205], v[36:39]
	v_mfma_f32_16x16x32_bf16 v[28:31], v[156:159], v[224:227], v[28:31]
	v_mfma_f32_16x16x32_bf16 v[20:23], v[170:173], v[224:227], v[20:23]
	s_waitcnt lgkmcnt(0)
	v_mfma_f32_16x16x32_bf16 v[12:15], v[156:159], v[240:243], v[12:15]
	v_mfma_f32_16x16x32_bf16 v[4:7], v[170:173], v[240:243], v[4:7]
	s_setprio 0
	s_setprio 1
	v_mfma_f32_16x16x32_bf16 v[56:59], v[174:177], v[190:193], 0
	v_mfma_f32_16x16x32_bf16 v[48:51], v[182:185], v[190:193], 0
	v_mfma_f32_16x16x32_bf16 v[40:43], v[174:177], v[198:201], 0
	v_mfma_f32_16x16x32_bf16 v[32:35], v[182:185], v[198:201], 0
	v_mfma_f32_16x16x32_bf16 v[24:27], v[174:177], v[220:223], 0
	v_mfma_f32_16x16x32_bf16 v[16:19], v[182:185], v[220:223], 0
	v_mfma_f32_16x16x32_bf16 v[8:11], v[174:177], v[228:231], 0
	v_mfma_f32_16x16x32_bf16 v[0:3], v[182:185], v[228:231], 0
	v_mfma_f32_16x16x32_bf16 v[56:59], v[178:181], v[194:197], v[56:59]
	v_mfma_f32_16x16x32_bf16 v[48:51], v[186:189], v[194:197], v[48:51]
	v_mfma_f32_16x16x32_bf16 v[40:43], v[178:181], v[202:205], v[40:43]
	v_mfma_f32_16x16x32_bf16 v[32:35], v[186:189], v[202:205], v[32:35]
	v_mfma_f32_16x16x32_bf16 v[24:27], v[178:181], v[224:227], v[24:27]
	v_mfma_f32_16x16x32_bf16 v[16:19], v[186:189], v[224:227], v[16:19]
	v_mfma_f32_16x16x32_bf16 v[8:11], v[178:181], v[240:243], v[8:11]
	v_mfma_f32_16x16x32_bf16 v[0:3], v[186:189], v[240:243], v[0:3]
	s_setprio 0
	s_cmp_eq_u32 s101, 0
	s_cbranch_scc1 .Lhbp_p5_3
	s_barrier
.Lhbp_p5_3:
	v_add_u32_e32 v164, 0x18000, v168
	ds_read_b128 v[152:155], v164
	ds_read_b128 v[156:159], v164 offset:1024
	ds_read_b128 v[160:163], v164 offset:2048
	ds_read_b128 v[170:173], v164 offset:3072
	v_add_u32_e32 v164, 0x1c000, v168
	ds_read_b128 v[174:177], v164
	ds_read_b128 v[178:181], v164 offset:1024
	ds_read_b128 v[182:185], v164 offset:2048
	ds_read_b128 v[186:189], v164 offset:3072
	ds_read_b128 v[190:193], v169 offset:32768
	ds_read_b128 v[194:197], v169 offset:33792
	ds_read_b128 v[198:201], v169 offset:34816
	ds_read_b128 v[202:205], v169 offset:35840
	ds_read_b128 v[220:223], v169 offset:36864
	ds_read_b128 v[224:227], v169 offset:37888
	ds_read_b128 v[228:231], v169 offset:38912
	ds_read_b128 v[240:243], v169 offset:39936
	s_add_i32 s56, s56, 0x80000
	s_mov_b32 m0, s12
	s_nop 0
	buffer_load_dwordx4 v166, s[24:27], s56 offen lds
	s_nop 0
	s_mov_b32 m0, s13
	s_nop 0
	buffer_load_dwordx4 v167, s[24:27], s56 offen lds
	s_waitcnt vmcnt(8)
	s_waitcnt lgkmcnt(0)
	s_cmp_lg_u32 s101, 0
	s_cbranch_scc1 .Lhbp_p5_4
	s_barrier
.Lhbp_p5_4:
	s_setprio 1
	s_waitcnt lgkmcnt(7)
	v_mfma_f32_16x16x32_bf16 v[148:151], v[152:155], v[190:193], v[148:151]
	v_mfma_f32_16x16x32_bf16 v[140:143], v[160:163], v[190:193], v[140:143]
	s_waitcnt lgkmcnt(5)
	v_mfma_f32_16x16x32_bf16 v[132:135], v[152:155], v[198:201], v[132:135]
	v_mfma_f32_16x16x32_bf16 v[124:127], v[160:163], v[198:201], v[124:127]
	s_waitcnt lgkmcnt(3)
	v_mfma_f32_16x16x32_bf16 v[116:119], v[152:155], v[220:223], v[116:119]
	v_mfma_f32_16x16x32_bf16 v[108:111], v[160:163], v[220:223], v[108:111]
	s_waitcnt lgkmcnt(1)
	v_mfma_f32_16x16x32_bf16 v[76:79], v[152:155], v[228:231], v[76:79]
	v_mfma_f32_16x16x32_bf16 v[68:71], v[160:163], v[228:231], v[68:71]
	v_mfma_f32_16x16x32_bf16 v[148:151], v[156:159], v[194:197], v[148:151]
	v_mfma_f32_16x16x32_bf16 v[140:143], v[170:173], v[194:197], v[140:143]
	v_mfma_f32_16x16x32_bf16 v[132:135], v[156:159], v[202:205], v[132:135]
	v_mfma_f32_16x16x32_bf16 v[124:127], v[170:173], v[202:205], v[124:127]
	v_mfma_f32_16x16x32_bf16 v[116:119], v[156:159], v[224:227], v[116:119]
	v_mfma_f32_16x16x32_bf16 v[108:111], v[170:173], v[224:227], v[108:111]
	s_waitcnt lgkmcnt(0)
	v_mfma_f32_16x16x32_bf16 v[76:79], v[156:159], v[240:243], v[76:79]
	v_mfma_f32_16x16x32_bf16 v[68:71], v[170:173], v[240:243], v[68:71]
	s_setprio 0
	s_setprio 1
	v_mfma_f32_16x16x32_bf16 v[144:147], v[174:177], v[190:193], v[144:147]
	v_mfma_f32_16x16x32_bf16 v[136:139], v[182:185], v[190:193], v[136:139]
	v_mfma_f32_16x16x32_bf16 v[128:131], v[174:177], v[198:201], v[128:131]
	v_mfma_f32_16x16x32_bf16 v[120:123], v[182:185], v[198:201], v[120:123]
	v_mfma_f32_16x16x32_bf16 v[112:115], v[174:177], v[220:223], v[112:115]
	v_mfma_f32_16x16x32_bf16 v[104:107], v[182:185], v[220:223], v[104:107]
	v_mfma_f32_16x16x32_bf16 v[72:75], v[174:177], v[228:231], v[72:75]
	v_mfma_f32_16x16x32_bf16 v[64:67], v[182:185], v[228:231], v[64:67]
	v_mfma_f32_16x16x32_bf16 v[144:147], v[178:181], v[194:197], v[144:147]
	v_mfma_f32_16x16x32_bf16 v[136:139], v[186:189], v[194:197], v[136:139]
	v_mfma_f32_16x16x32_bf16 v[128:131], v[178:181], v[202:205], v[128:131]
	v_mfma_f32_16x16x32_bf16 v[120:123], v[186:189], v[202:205], v[120:123]
	v_mfma_f32_16x16x32_bf16 v[112:115], v[178:181], v[224:227], v[112:115]
	v_mfma_f32_16x16x32_bf16 v[104:107], v[186:189], v[224:227], v[104:107]
	v_mfma_f32_16x16x32_bf16 v[72:75], v[178:181], v[240:243], v[72:75]
	v_mfma_f32_16x16x32_bf16 v[64:67], v[186:189], v[240:243], v[64:67]
	s_setprio 0
	s_cmp_eq_u32 s101, 0
	s_cbranch_scc1 .Lhbp_p5_5
	s_barrier
.Lhbp_p5_5:
	ds_read_b128 v[190:193], v169 offset:49152
	ds_read_b128 v[194:197], v169 offset:50176
	ds_read_b128 v[198:201], v169 offset:51200
	ds_read_b128 v[202:205], v169 offset:52224
	ds_read_b128 v[220:223], v169 offset:53248
	ds_read_b128 v[224:227], v169 offset:54272
	ds_read_b128 v[228:231], v169 offset:55296
	ds_read_b128 v[240:243], v169 offset:56320
	s_or_b32 s56, s55, 0x4000
	s_mov_b32 m0, s16
	s_nop 0
	buffer_load_dwordx4 v166, s[28:31], s56 offen lds
	s_add_i32 s55, s55, 0x84000
	s_mov_b32 m0, s17
	s_nop 0
	buffer_load_dwordx4 v167, s[28:31], s56 offen lds
	s_nop 0
	s_mov_b32 m0, s34
	s_nop 0
	buffer_load_dwordx4 v166, s[28:31], s55 offen lds
	s_nop 0
	s_mov_b32 m0, s40
	s_nop 0
	buffer_load_dwordx4 v167, s[28:31], s55 offen lds
	s_nop 0
	s_mov_b32 m0, s18
	s_nop 0
	buffer_load_dwordx4 v166, s[24:27], s53 offen lds
	s_nop 0
	s_mov_b32 m0, s19
	s_nop 0
	buffer_load_dwordx4 v167, s[24:27], s53 offen lds
	s_waitcnt vmcnt(8)
	s_waitcnt lgkmcnt(0)
	s_cmp_lg_u32 s101, 0
	s_cbranch_scc1 .Lhbp_p5_6
	s_barrier
.Lhbp_p5_6:
	s_setprio 1
	s_waitcnt lgkmcnt(7)
	v_mfma_f32_16x16x32_bf16 v[60:63], v[152:155], v[190:193], v[60:63]
	v_mfma_f32_16x16x32_bf16 v[52:55], v[160:163], v[190:193], v[52:55]
	s_waitcnt lgkmcnt(5)
	v_mfma_f32_16x16x32_bf16 v[44:47], v[152:155], v[198:201], v[44:47]
	v_mfma_f32_16x16x32_bf16 v[36:39], v[160:163], v[198:201], v[36:39]
	s_waitcnt lgkmcnt(3)
	v_mfma_f32_16x16x32_bf16 v[28:31], v[152:155], v[220:223], v[28:31]
	v_mfma_f32_16x16x32_bf16 v[20:23], v[160:163], v[220:223], v[20:23]
	s_waitcnt lgkmcnt(1)
	v_mfma_f32_16x16x32_bf16 v[12:15], v[152:155], v[228:231], v[12:15]
	v_mfma_f32_16x16x32_bf16 v[4:7], v[160:163], v[228:231], v[4:7]
	v_mfma_f32_16x16x32_bf16 v[60:63], v[156:159], v[194:197], v[60:63]
	v_mfma_f32_16x16x32_bf16 v[52:55], v[170:173], v[194:197], v[52:55]
	v_mfma_f32_16x16x32_bf16 v[44:47], v[156:159], v[202:205], v[44:47]
	v_mfma_f32_16x16x32_bf16 v[36:39], v[170:173], v[202:205], v[36:39]
	v_mfma_f32_16x16x32_bf16 v[28:31], v[156:159], v[224:227], v[28:31]
	v_mfma_f32_16x16x32_bf16 v[20:23], v[170:173], v[224:227], v[20:23]
	s_waitcnt lgkmcnt(0)
	v_mfma_f32_16x16x32_bf16 v[12:15], v[156:159], v[240:243], v[12:15]
	v_mfma_f32_16x16x32_bf16 v[4:7], v[170:173], v[240:243], v[4:7]
	s_setprio 0
	s_setprio 1
	v_mfma_f32_16x16x32_bf16 v[56:59], v[174:177], v[190:193], v[56:59]
	v_mfma_f32_16x16x32_bf16 v[48:51], v[182:185], v[190:193], v[48:51]
	v_mfma_f32_16x16x32_bf16 v[40:43], v[174:177], v[198:201], v[40:43]
	v_mfma_f32_16x16x32_bf16 v[32:35], v[182:185], v[198:201], v[32:35]
	v_mfma_f32_16x16x32_bf16 v[24:27], v[174:177], v[220:223], v[24:27]
	v_mfma_f32_16x16x32_bf16 v[16:19], v[182:185], v[220:223], v[16:19]
	v_mfma_f32_16x16x32_bf16 v[8:11], v[174:177], v[228:231], v[8:11]
	v_mfma_f32_16x16x32_bf16 v[0:3], v[182:185], v[228:231], v[0:3]
	v_mfma_f32_16x16x32_bf16 v[56:59], v[178:181], v[194:197], v[56:59]
	v_mfma_f32_16x16x32_bf16 v[48:51], v[186:189], v[194:197], v[48:51]
	v_mfma_f32_16x16x32_bf16 v[40:43], v[178:181], v[202:205], v[40:43]
	v_mfma_f32_16x16x32_bf16 v[32:35], v[186:189], v[202:205], v[32:35]
	v_mfma_f32_16x16x32_bf16 v[24:27], v[178:181], v[224:227], v[24:27]
	v_mfma_f32_16x16x32_bf16 v[16:19], v[186:189], v[224:227], v[16:19]
	v_mfma_f32_16x16x32_bf16 v[8:11], v[178:181], v[240:243], v[8:11]
	v_mfma_f32_16x16x32_bf16 v[0:3], v[186:189], v[240:243], v[0:3]
	s_setprio 0
	s_cmp_eq_u32 s101, 0
	s_cbranch_scc1 .Lhbp_p5_7
	s_barrier
.Lhbp_p5_7:
	s_add_i32 s52, s52, 2
	s_add_i32 s37, s37, 0x8000
	s_add_i32 s51, s51, 0x8000
.LBB0_795:
	v_add_u32_e32 v164, 0x10000, v168
	ds_read_b128 v[152:155], v164
	ds_read_b128 v[156:159], v164 offset:1024
	ds_read_b128 v[160:163], v164 offset:2048
	ds_read_b128 v[170:173], v164 offset:3072
	v_add_u32_e32 v164, 0x14000, v168
	ds_read_b128 v[174:177], v164
	ds_read_b128 v[178:181], v164 offset:1024
	ds_read_b128 v[182:185], v164 offset:2048
	ds_read_b128 v[186:189], v164 offset:3072
	s_add_i32 s53, s37, 0xfff84000
	s_cmp_eq_u32 s52, 28
	s_cselect_b32 s56, s4, s53
	s_cselect_b32 s55, s5, s51
	s_or_b32 s53, s56, 0x4000
	ds_read_b128 v[190:193], v169
	ds_read_b128 v[194:197], v169 offset:1024
	ds_read_b128 v[198:201], v169 offset:2048
	ds_read_b128 v[202:205], v169 offset:3072
	ds_read_b128 v[220:223], v169 offset:4096
	ds_read_b128 v[224:227], v169 offset:5120
	ds_read_b128 v[228:231], v169 offset:6144
	ds_read_b128 v[240:243], v169 offset:7168
	s_mov_b32 m0, s41
	s_nop 0
	buffer_load_dwordx4 v166, s[24:27], s37 offen lds
	s_nop 0
	s_mov_b32 m0, s42
	s_nop 0
	buffer_load_dwordx4 v167, s[24:27], s37 offen lds
	s_waitcnt vmcnt(8)
	s_waitcnt lgkmcnt(0)
	s_cmp_lg_u32 s101, 0
	s_cbranch_scc1 .Lhb_p5_0
	s_barrier

.Lhb_p5_1:
	ds_read_b128 v[190:193], v169 offset:16384
	ds_read_b128 v[194:197], v169 offset:17408
	ds_read_b128 v[198:201], v169 offset:18432
	ds_read_b128 v[202:205], v169 offset:19456
	ds_read_b128 v[220:223], v169 offset:20480
	ds_read_b128 v[224:227], v169 offset:21504
	ds_read_b128 v[228:231], v169 offset:22528
	ds_read_b128 v[240:243], v169 offset:23552
	s_mov_b32 m0, s7
	s_nop 0
	buffer_load_dwordx4 v166, s[28:31], s55 offen lds
	s_add_i32 s57, s55, 0x80000
	s_mov_b32 m0, s8
	s_nop 0
	buffer_load_dwordx4 v167, s[28:31], s55 offen lds
	s_nop 0
	s_mov_b32 m0, s9
	s_nop 0
	buffer_load_dwordx4 v166, s[28:31], s57 offen lds
	s_nop 0
	s_mov_b32 m0, s10
	s_nop 0
	buffer_load_dwordx4 v167, s[28:31], s57 offen lds
	s_nop 0
	s_mov_b32 m0, s6
	s_nop 0
	buffer_load_dwordx4 v166, s[24:27], s56 offen lds
	s_nop 0
	s_mov_b32 m0, s11
	s_nop 0
	buffer_load_dwordx4 v167, s[24:27], s56 offen lds
	s_waitcnt vmcnt(8)
	s_waitcnt lgkmcnt(0)
	s_cmp_lg_u32 s101, 0
	s_cbranch_scc1 .Lhb_p5_2
	s_barrier

.Lhb_p5_7:
	s_add_i32 s52, s52, 2
	s_add_i32 s37, s37, 0x8000
	s_add_i32 s51, s51, 0x8000
	s_cmp_gt_u32 s52, 29
	s_cbranch_scc0 .LBB0_795
	s_and_b64 vcc, exec, s[2:3]
	s_cbranch_vccz .LBB0_798
	s_nop 0
.LBB0_798:
	s_lshl_b32 s51, s36, 15
	s_lshl_b32 s4, s33, 11
	s_add_u32 s4, s14, s4
	s_addc_u32 s5, s15, 0
	s_mov_b64 s[36:37], s[4:5]
	v_pk_mul_f32 v[146:147], v[150:151], v[146:147]
	v_lshl_add_u64 v[152:153], s[36:37], 0, v[80:81]
	global_load_dwordx2 v[170:171], v[152:153], off
	s_add_u32 s36, s4, 0x80
	s_addc_u32 s37, s5, 0
	v_pk_mul_f32 v[144:145], v[148:149], v[144:145]
	v_lshl_add_u64 v[152:153], s[36:37], 0, v[80:81]
	global_load_dwordx2 v[164:165], v[152:153], off
	s_add_u32 s36, s4, 0x100
	s_addc_u32 s37, s5, 0
	s_mul_i32 s33, s33, 0x2c0000
	v_lshl_add_u64 v[152:153], s[36:37], 0, v[80:81]
	global_load_dwordx2 v[162:163], v[152:153], off
	s_add_u32 s36, s4, 0x180
	s_addc_u32 s37, s5, 0
	v_pk_mul_f32 v[138:139], v[142:143], v[138:139]
	v_lshl_add_u64 v[152:153], s[36:37], 0, v[80:81]
	global_load_dwordx2 v[160:161], v[152:153], off
	s_add_u32 s36, s4, 0x400
	s_addc_u32 s37, s5, 0
	v_pk_mul_f32 v[136:137], v[140:141], v[136:137]
	v_lshl_add_u64 v[152:153], s[36:37], 0, v[80:81]
	s_add_u32 s36, s4, 0x480
	s_addc_u32 s37, s5, 0
	global_load_dwordx2 v[158:159], v[152:153], off
	v_pk_mul_f32 v[130:131], v[134:135], v[130:131]
	v_lshl_add_u64 v[152:153], s[36:37], 0, v[80:81]
	s_add_u32 s36, s4, 0x500
	s_addc_u32 s37, s5, 0
	s_add_u32 s4, s4, 0x580
	global_load_dwordx2 v[156:157], v[152:153], off
	s_addc_u32 s5, s5, 0
	v_lshl_add_u64 v[152:153], s[36:37], 0, v[80:81]
	global_load_dwordx2 v[154:155], v[152:153], off
	s_add_i32 s33, s33, s51
	v_lshl_add_u64 v[152:153], s[4:5], 0, v[80:81]
	global_load_dwordx2 v[152:153], v[152:153], off
	s_add_u32 s4, s20, s33
	s_addc_u32 s5, s68, 0
	s_mov_b64 s[36:37], s[4:5]
	v_pk_mul_f32 v[128:129], v[132:133], v[128:129]
	v_pk_mul_f32 v[122:123], v[126:127], v[122:123]
	v_pk_mul_f32 v[120:121], v[124:125], v[120:121]
	s_add_u32 s4, s4, 0x800
	s_addc_u32 s5, s5, 0
	v_pk_mul_f32 v[114:115], v[118:119], v[114:115]
	v_pk_mul_f32 v[112:113], v[116:117], v[112:113]
	v_pk_mul_f32 v[106:107], v[110:111], v[106:107]
	v_pk_mul_f32 v[104:105], v[108:109], v[104:105]
	v_pk_mul_f32 v[74:75], v[78:79], v[74:75]
	v_pk_mul_f32 v[72:73], v[76:77], v[72:73]
	v_pk_mul_f32 v[66:67], v[70:71], v[66:67]
	v_pk_mul_f32 v[64:65], v[68:69], v[64:65]
	v_pk_mul_f32 v[58:59], v[62:63], v[58:59]
	v_pk_mul_f32 v[56:57], v[60:61], v[56:57]
	v_pk_mul_f32 v[50:51], v[54:55], v[50:51]
	v_pk_mul_f32 v[48:49], v[52:53], v[48:49]
	v_pk_mul_f32 v[42:43], v[46:47], v[42:43]
	v_pk_mul_f32 v[40:41], v[44:45], v[40:41]
	v_pk_mul_f32 v[34:35], v[38:39], v[34:35]
	v_pk_mul_f32 v[32:33], v[36:37], v[32:33]
	v_pk_mul_f32 v[26:27], v[30:31], v[26:27]
	v_pk_mul_f32 v[24:25], v[28:29], v[24:25]
	v_pk_mul_f32 v[18:19], v[22:23], v[18:19]
	v_pk_mul_f32 v[16:17], v[20:21], v[16:17]
	v_pk_mul_f32 v[10:11], v[14:15], v[10:11]
	v_pk_mul_f32 v[8:9], v[12:13], v[8:9]
	v_pk_mul_f32 v[2:3], v[6:7], v[2:3]
	v_pk_mul_f32 v[0:1], v[4:5], v[0:1]
	s_waitcnt vmcnt(7)
	v_cvt_f32_u32_e32 v171, v171
	v_cvt_f32_u32_e32 v170, v170
	v_fmac_f32_e32 v170, 0x4f800000, v171
	v_fmamk_f32 v170, v170, 0x30000000, v234
	v_rsq_f32_e32 v178, v170
	s_nop 0
	v_mul_f32_e32 v174, 0xbfb8aa3b, v178
	v_pk_mul_f32 v[172:173], v[150:151], v[174:175] op_sel_hi:[1,0]
	v_pk_mul_f32 v[170:171], v[148:149], v[174:175] op_sel_hi:[1,0]
	v_pk_mul_f32 v[176:177], v[142:143], v[174:175] op_sel_hi:[1,0]
	v_pk_mul_f32 v[174:175], v[140:141], v[174:175] op_sel_hi:[1,0]
	v_mul_f32_e32 v178, v178, v178
	v_pk_mul_f32 v[180:181], v[146:147], v[178:179] op_sel_hi:[1,0]
	v_exp_f32_e32 v170, v170
	v_exp_f32_e32 v174, v174
	v_exp_f32_e32 v171, v171
	v_exp_f32_e32 v175, v175
	v_exp_f32_e32 v172, v172
	v_exp_f32_e32 v176, v176
	v_exp_f32_e32 v173, v173
	v_exp_f32_e32 v177, v177
	v_pk_mul_f32 v[182:183], v[144:145], v[178:179] op_sel_hi:[1,0]
	v_pk_add_f32 v[144:145], v[170:171], 1.0 op_sel_hi:[1,0]
	v_pk_add_f32 v[146:147], v[172:173], 1.0 op_sel_hi:[1,0]
	v_pk_add_f32 v[150:151], v[176:177], 1.0 op_sel_hi:[1,0]
	v_pk_add_f32 v[148:149], v[174:175], 1.0 op_sel_hi:[1,0]
	v_pk_mul_f32 v[138:139], v[138:139], v[178:179] op_sel_hi:[1,0]
	v_pk_mul_f32 v[136:137], v[136:137], v[178:179] op_sel_hi:[1,0]
	v_rcp_f32_e32 v144, v144
	v_rcp_f32_e32 v148, v148
	v_rcp_f32_e32 v145, v145
	v_rcp_f32_e32 v149, v149
	v_rcp_f32_e32 v146, v146
	v_rcp_f32_e32 v150, v150
	v_rcp_f32_e32 v147, v147
	v_rcp_f32_e32 v151, v151
	s_nop 0
	v_pk_mul_f32 v[140:141], v[180:181], v[146:147]
	v_pk_mul_f32 v[142:143], v[182:183], v[144:145]
	v_pk_mul_f32 v[144:145], v[138:139], v[150:151]
	v_pk_mul_f32 v[138:139], v[136:137], v[148:149]
	v_cvt_pk_bf16_f32 v136, v142, v143
	v_cvt_pk_bf16_f32 v137, v140, v141
	v_cvt_pk_bf16_f32 v138, v138, v139
	v_cvt_pk_bf16_f32 v139, v144, v145
	v_lshl_add_u64 v[140:141], s[36:37], 0, v[82:83]
	global_store_dwordx4 v[140:141], v[136:139], off nt
	s_waitcnt vmcnt(7)
	s_nop 0
	v_cvt_f32_u32_e32 v136, v165
	v_cvt_f32_u32_e32 v137, v164
	v_fmac_f32_e32 v137, 0x4f800000, v136
	v_fmamk_f32 v136, v137, 0x30000000, v234
	v_rsq_f32_e32 v144, v136
	s_nop 0
	v_mul_f32_e32 v140, 0xbfb8aa3b, v144
	v_pk_mul_f32 v[138:139], v[134:135], v[140:141] op_sel_hi:[1,0]
	v_pk_mul_f32 v[136:137], v[132:133], v[140:141] op_sel_hi:[1,0]
	v_pk_mul_f32 v[142:143], v[126:127], v[140:141] op_sel_hi:[1,0]
	v_pk_mul_f32 v[140:141], v[124:125], v[140:141] op_sel_hi:[1,0]
	v_mul_f32_e32 v144, v144, v144
	v_pk_mul_f32 v[146:147], v[130:131], v[144:145] op_sel_hi:[1,0]
	v_exp_f32_e32 v136, v136
	v_exp_f32_e32 v140, v140
	v_exp_f32_e32 v137, v137
	v_exp_f32_e32 v141, v141
	v_exp_f32_e32 v138, v138
	v_exp_f32_e32 v142, v142
	v_exp_f32_e32 v139, v139
	v_exp_f32_e32 v143, v143
	v_pk_mul_f32 v[148:149], v[128:129], v[144:145] op_sel_hi:[1,0]
	v_pk_add_f32 v[128:129], v[136:137], 1.0 op_sel_hi:[1,0]
	v_pk_add_f32 v[130:131], v[138:139], 1.0 op_sel_hi:[1,0]
	v_pk_add_f32 v[134:135], v[142:143], 1.0 op_sel_hi:[1,0]
	v_pk_add_f32 v[132:133], v[140:141], 1.0 op_sel_hi:[1,0]
	v_pk_mul_f32 v[122:123], v[122:123], v[144:145] op_sel_hi:[1,0]
	v_pk_mul_f32 v[120:121], v[120:121], v[144:145] op_sel_hi:[1,0]
	v_rcp_f32_e32 v128, v128
	v_rcp_f32_e32 v132, v132
	v_rcp_f32_e32 v129, v129
	v_rcp_f32_e32 v133, v133
	v_rcp_f32_e32 v130, v130
	v_rcp_f32_e32 v134, v134
	v_rcp_f32_e32 v131, v131
	v_rcp_f32_e32 v135, v135
	s_nop 0
	v_pk_mul_f32 v[124:125], v[146:147], v[130:131]
	v_pk_mul_f32 v[126:127], v[148:149], v[128:129]
	v_pk_mul_f32 v[128:129], v[122:123], v[134:135]
	v_pk_mul_f32 v[122:123], v[120:121], v[132:133]
	v_cvt_pk_bf16_f32 v120, v126, v127
	v_cvt_pk_bf16_f32 v121, v124, v125
	v_cvt_pk_bf16_f32 v122, v122, v123
	v_cvt_pk_bf16_f32 v123, v128, v129
	v_lshl_add_u64 v[124:125], s[4:5], 0, v[82:83]
	global_store_dwordx4 v[124:125], v[120:123], off nt
	s_or_b32 s4, s33, 0x1000
	s_add_u32 s4, s20, s4
	s_waitcnt vmcnt(7)
	v_cvt_f32_u32_e32 v120, v163
	v_cvt_f32_u32_e32 v121, v162
	s_addc_u32 s5, s68, 0
	v_fmac_f32_e32 v121, 0x4f800000, v120
	v_fmamk_f32 v120, v121, 0x30000000, v234
	v_rsq_f32_e32 v128, v120
	s_nop 0
	v_mul_f32_e32 v124, 0xbfb8aa3b, v128
	v_pk_mul_f32 v[122:123], v[118:119], v[124:125] op_sel_hi:[1,0]
	v_pk_mul_f32 v[120:121], v[116:117], v[124:125] op_sel_hi:[1,0]
	v_pk_mul_f32 v[126:127], v[110:111], v[124:125] op_sel_hi:[1,0]
	v_pk_mul_f32 v[124:125], v[108:109], v[124:125] op_sel_hi:[1,0]
	v_mul_f32_e32 v128, v128, v128
	v_pk_mul_f32 v[130:131], v[114:115], v[128:129] op_sel_hi:[1,0]
	v_exp_f32_e32 v120, v120
	v_exp_f32_e32 v124, v124
	v_exp_f32_e32 v121, v121
	v_exp_f32_e32 v125, v125
	v_exp_f32_e32 v122, v122
	v_exp_f32_e32 v126, v126
	v_exp_f32_e32 v123, v123
	v_exp_f32_e32 v127, v127
	v_pk_mul_f32 v[132:133], v[112:113], v[128:129] op_sel_hi:[1,0]
	v_pk_add_f32 v[112:113], v[120:121], 1.0 op_sel_hi:[1,0]
	v_pk_add_f32 v[114:115], v[122:123], 1.0 op_sel_hi:[1,0]
	v_pk_add_f32 v[118:119], v[126:127], 1.0 op_sel_hi:[1,0]
	v_pk_add_f32 v[116:117], v[124:125], 1.0 op_sel_hi:[1,0]
	v_pk_mul_f32 v[106:107], v[106:107], v[128:129] op_sel_hi:[1,0]
	v_pk_mul_f32 v[104:105], v[104:105], v[128:129] op_sel_hi:[1,0]
	v_rcp_f32_e32 v112, v112
	v_rcp_f32_e32 v116, v116
	v_rcp_f32_e32 v113, v113
	v_rcp_f32_e32 v117, v117
	v_rcp_f32_e32 v114, v114
	v_rcp_f32_e32 v118, v118
	v_rcp_f32_e32 v115, v115
	v_rcp_f32_e32 v119, v119
	s_nop 0
	v_pk_mul_f32 v[108:109], v[130:131], v[114:115]
	v_pk_mul_f32 v[110:111], v[132:133], v[112:113]
	v_pk_mul_f32 v[112:113], v[106:107], v[118:119]
	v_pk_mul_f32 v[106:107], v[104:105], v[116:117]
	v_cvt_pk_bf16_f32 v104, v110, v111
	v_cvt_pk_bf16_f32 v105, v108, v109
	v_cvt_pk_bf16_f32 v106, v106, v107
	v_cvt_pk_bf16_f32 v107, v112, v113
	v_lshl_add_u64 v[108:109], s[4:5], 0, v[82:83]
	global_store_dwordx4 v[108:109], v[104:107], off nt
	s_or_b32 s4, s33, 0x1800
	s_add_u32 s4, s20, s4
	s_waitcnt vmcnt(7)
	v_cvt_f32_u32_e32 v104, v161
	v_cvt_f32_u32_e32 v105, v160
	s_addc_u32 s5, s68, 0
	v_fmac_f32_e32 v105, 0x4f800000, v104
	v_fmamk_f32 v104, v105, 0x30000000, v234
	v_rsq_f32_e32 v112, v104
	s_nop 0
	v_mul_f32_e32 v108, 0xbfb8aa3b, v112
	v_pk_mul_f32 v[106:107], v[78:79], v[108:109] op_sel_hi:[1,0]
	v_pk_mul_f32 v[104:105], v[76:77], v[108:109] op_sel_hi:[1,0]
	v_pk_mul_f32 v[110:111], v[70:71], v[108:109] op_sel_hi:[1,0]
	v_pk_mul_f32 v[108:109], v[68:69], v[108:109] op_sel_hi:[1,0]
	v_mul_f32_e32 v112, v112, v112
	v_pk_mul_f32 v[114:115], v[74:75], v[112:113] op_sel_hi:[1,0]
	v_exp_f32_e32 v104, v104
	v_exp_f32_e32 v108, v108
	v_exp_f32_e32 v105, v105
	v_exp_f32_e32 v109, v109
	v_exp_f32_e32 v106, v106
	v_exp_f32_e32 v110, v110
	v_exp_f32_e32 v107, v107
	v_exp_f32_e32 v111, v111
	v_pk_mul_f32 v[116:117], v[72:73], v[112:113] op_sel_hi:[1,0]
	v_pk_add_f32 v[72:73], v[104:105], 1.0 op_sel_hi:[1,0]
	v_pk_add_f32 v[74:75], v[106:107], 1.0 op_sel_hi:[1,0]
	v_pk_add_f32 v[78:79], v[110:111], 1.0 op_sel_hi:[1,0]
	v_pk_add_f32 v[76:77], v[108:109], 1.0 op_sel_hi:[1,0]
	v_pk_mul_f32 v[66:67], v[66:67], v[112:113] op_sel_hi:[1,0]
	v_pk_mul_f32 v[64:65], v[64:65], v[112:113] op_sel_hi:[1,0]
	v_rcp_f32_e32 v72, v72
	v_rcp_f32_e32 v76, v76
	v_rcp_f32_e32 v73, v73
	v_rcp_f32_e32 v77, v77
	v_rcp_f32_e32 v74, v74
	v_rcp_f32_e32 v78, v78
	v_rcp_f32_e32 v75, v75
	v_rcp_f32_e32 v79, v79
	s_nop 0
	v_pk_mul_f32 v[68:69], v[114:115], v[74:75]
	v_pk_mul_f32 v[70:71], v[116:117], v[72:73]
	v_pk_mul_f32 v[72:73], v[66:67], v[78:79]
	v_pk_mul_f32 v[66:67], v[64:65], v[76:77]
	v_cvt_pk_bf16_f32 v64, v70, v71
	v_cvt_pk_bf16_f32 v65, v68, v69
	v_cvt_pk_bf16_f32 v66, v66, v67
	v_cvt_pk_bf16_f32 v67, v72, v73
	v_lshl_add_u64 v[68:69], s[4:5], 0, v[82:83]
	global_store_dwordx4 v[68:69], v[64:67], off nt
	s_add_i32 s4, s33, 0x160000
	s_add_u32 s4, s20, s4
	s_waitcnt vmcnt(7)
	v_cvt_f32_u32_e32 v64, v159
	v_cvt_f32_u32_e32 v65, v158
	s_addc_u32 s5, s68, 0
	v_fmac_f32_e32 v65, 0x4f800000, v64
	v_fmamk_f32 v64, v65, 0x30000000, v234
	v_rsq_f32_e32 v72, v64
	s_nop 0
	v_mul_f32_e32 v68, 0xbfb8aa3b, v72
	v_pk_mul_f32 v[66:67], v[62:63], v[68:69] op_sel_hi:[1,0]
	v_pk_mul_f32 v[64:65], v[60:61], v[68:69] op_sel_hi:[1,0]
	v_pk_mul_f32 v[70:71], v[54:55], v[68:69] op_sel_hi:[1,0]
	v_pk_mul_f32 v[68:69], v[52:53], v[68:69] op_sel_hi:[1,0]
	v_mul_f32_e32 v72, v72, v72
	v_pk_mul_f32 v[74:75], v[58:59], v[72:73] op_sel_hi:[1,0]
	v_exp_f32_e32 v64, v64
	v_exp_f32_e32 v68, v68
	v_exp_f32_e32 v65, v65
	v_exp_f32_e32 v69, v69
	v_exp_f32_e32 v66, v66
	v_exp_f32_e32 v70, v70
	v_exp_f32_e32 v67, v67
	v_exp_f32_e32 v71, v71
	v_pk_mul_f32 v[76:77], v[56:57], v[72:73] op_sel_hi:[1,0]
	v_pk_add_f32 v[56:57], v[64:65], 1.0 op_sel_hi:[1,0]
	v_pk_add_f32 v[58:59], v[66:67], 1.0 op_sel_hi:[1,0]
	v_pk_add_f32 v[62:63], v[70:71], 1.0 op_sel_hi:[1,0]
	v_pk_add_f32 v[60:61], v[68:69], 1.0 op_sel_hi:[1,0]
	v_pk_mul_f32 v[50:51], v[50:51], v[72:73] op_sel_hi:[1,0]
	v_pk_mul_f32 v[48:49], v[48:49], v[72:73] op_sel_hi:[1,0]
	v_rcp_f32_e32 v56, v56
	v_rcp_f32_e32 v60, v60
	v_rcp_f32_e32 v57, v57
	v_rcp_f32_e32 v61, v61
	v_rcp_f32_e32 v58, v58
	v_rcp_f32_e32 v62, v62
	v_rcp_f32_e32 v59, v59
	v_rcp_f32_e32 v63, v63
	s_nop 0
	v_pk_mul_f32 v[52:53], v[74:75], v[58:59]
	v_pk_mul_f32 v[54:55], v[76:77], v[56:57]
	v_pk_mul_f32 v[56:57], v[50:51], v[62:63]
	v_pk_mul_f32 v[50:51], v[48:49], v[60:61]
	v_cvt_pk_bf16_f32 v48, v54, v55
	v_cvt_pk_bf16_f32 v49, v52, v53
	v_cvt_pk_bf16_f32 v50, v50, v51
	v_cvt_pk_bf16_f32 v51, v56, v57
	v_lshl_add_u64 v[52:53], s[4:5], 0, v[82:83]
	global_store_dwordx4 v[52:53], v[48:51], off nt
	s_add_i32 s4, s33, 0x160800
	s_add_u32 s4, s20, s4
	s_waitcnt vmcnt(7)
	v_cvt_f32_u32_e32 v48, v157
	v_cvt_f32_u32_e32 v49, v156
	s_addc_u32 s5, s68, 0
	v_fmac_f32_e32 v49, 0x4f800000, v48
	v_fmamk_f32 v48, v49, 0x30000000, v234
	v_rsq_f32_e32 v56, v48
	s_nop 0
	v_mul_f32_e32 v52, 0xbfb8aa3b, v56
	v_pk_mul_f32 v[50:51], v[46:47], v[52:53] op_sel_hi:[1,0]
	v_pk_mul_f32 v[48:49], v[44:45], v[52:53] op_sel_hi:[1,0]
	v_pk_mul_f32 v[54:55], v[38:39], v[52:53] op_sel_hi:[1,0]
	v_pk_mul_f32 v[52:53], v[36:37], v[52:53] op_sel_hi:[1,0]
	v_mul_f32_e32 v56, v56, v56
	v_pk_mul_f32 v[58:59], v[42:43], v[56:57] op_sel_hi:[1,0]
	v_exp_f32_e32 v48, v48
	v_exp_f32_e32 v52, v52
	v_exp_f32_e32 v49, v49
	v_exp_f32_e32 v53, v53
	v_exp_f32_e32 v50, v50
	v_exp_f32_e32 v54, v54
	v_exp_f32_e32 v51, v51
	v_exp_f32_e32 v55, v55
	v_pk_mul_f32 v[60:61], v[40:41], v[56:57] op_sel_hi:[1,0]
	v_pk_add_f32 v[40:41], v[48:49], 1.0 op_sel_hi:[1,0]
	v_pk_add_f32 v[42:43], v[50:51], 1.0 op_sel_hi:[1,0]
	v_pk_add_f32 v[46:47], v[54:55], 1.0 op_sel_hi:[1,0]
	v_pk_add_f32 v[44:45], v[52:53], 1.0 op_sel_hi:[1,0]
	v_pk_mul_f32 v[34:35], v[34:35], v[56:57] op_sel_hi:[1,0]
	v_pk_mul_f32 v[32:33], v[32:33], v[56:57] op_sel_hi:[1,0]
	v_rcp_f32_e32 v40, v40
	v_rcp_f32_e32 v44, v44
	v_rcp_f32_e32 v41, v41
	v_rcp_f32_e32 v45, v45
	v_rcp_f32_e32 v42, v42
	v_rcp_f32_e32 v46, v46
	v_rcp_f32_e32 v43, v43
	v_rcp_f32_e32 v47, v47
	s_nop 0
	v_pk_mul_f32 v[36:37], v[58:59], v[42:43]
	v_pk_mul_f32 v[38:39], v[60:61], v[40:41]
	v_pk_mul_f32 v[40:41], v[34:35], v[46:47]
	v_pk_mul_f32 v[34:35], v[32:33], v[44:45]
	v_cvt_pk_bf16_f32 v32, v38, v39
	v_cvt_pk_bf16_f32 v33, v36, v37
	v_cvt_pk_bf16_f32 v34, v34, v35
	v_cvt_pk_bf16_f32 v35, v40, v41
	v_lshl_add_u64 v[36:37], s[4:5], 0, v[82:83]
	global_store_dwordx4 v[36:37], v[32:35], off nt
	s_add_i32 s4, s33, 0x161000
	s_add_u32 s4, s20, s4
	s_waitcnt vmcnt(7)
	v_cvt_f32_u32_e32 v32, v155
	v_cvt_f32_u32_e32 v33, v154
	s_addc_u32 s5, s68, 0
	s_add_i32 s33, s33, 0x161800
	v_fmac_f32_e32 v33, 0x4f800000, v32
	v_fmamk_f32 v32, v33, 0x30000000, v234
	v_rsq_f32_e32 v40, v32
	s_nop 0
	v_mul_f32_e32 v36, 0xbfb8aa3b, v40
	v_pk_mul_f32 v[34:35], v[30:31], v[36:37] op_sel_hi:[1,0]
	v_pk_mul_f32 v[32:33], v[28:29], v[36:37] op_sel_hi:[1,0]
	v_pk_mul_f32 v[38:39], v[22:23], v[36:37] op_sel_hi:[1,0]
	v_pk_mul_f32 v[36:37], v[20:21], v[36:37] op_sel_hi:[1,0]
	v_mul_f32_e32 v40, v40, v40
	v_pk_mul_f32 v[42:43], v[26:27], v[40:41] op_sel_hi:[1,0]
	v_exp_f32_e32 v32, v32
	v_exp_f32_e32 v36, v36
	v_exp_f32_e32 v33, v33
	v_exp_f32_e32 v37, v37
	v_exp_f32_e32 v34, v34
	v_exp_f32_e32 v38, v38
	v_exp_f32_e32 v35, v35
	v_exp_f32_e32 v39, v39
	v_pk_mul_f32 v[44:45], v[24:25], v[40:41] op_sel_hi:[1,0]
	v_pk_add_f32 v[24:25], v[32:33], 1.0 op_sel_hi:[1,0]
	v_pk_add_f32 v[26:27], v[34:35], 1.0 op_sel_hi:[1,0]
	v_pk_add_f32 v[30:31], v[38:39], 1.0 op_sel_hi:[1,0]
	v_pk_add_f32 v[28:29], v[36:37], 1.0 op_sel_hi:[1,0]
	v_pk_mul_f32 v[18:19], v[18:19], v[40:41] op_sel_hi:[1,0]
	v_pk_mul_f32 v[16:17], v[16:17], v[40:41] op_sel_hi:[1,0]
	v_rcp_f32_e32 v24, v24
	v_rcp_f32_e32 v28, v28
	v_rcp_f32_e32 v25, v25
	v_rcp_f32_e32 v29, v29
	v_rcp_f32_e32 v26, v26
	v_rcp_f32_e32 v30, v30
	v_rcp_f32_e32 v27, v27
	v_rcp_f32_e32 v31, v31
	s_nop 0
	v_pk_mul_f32 v[20:21], v[42:43], v[26:27]
	v_pk_mul_f32 v[22:23], v[44:45], v[24:25]
	v_pk_mul_f32 v[24:25], v[18:19], v[30:31]
	v_pk_mul_f32 v[18:19], v[16:17], v[28:29]
	v_cvt_pk_bf16_f32 v16, v22, v23
	v_cvt_pk_bf16_f32 v17, v20, v21
	v_cvt_pk_bf16_f32 v18, v18, v19
	v_cvt_pk_bf16_f32 v19, v24, v25
	v_lshl_add_u64 v[20:21], s[4:5], 0, v[82:83]
	global_store_dwordx4 v[20:21], v[16:19], off nt
	s_add_u32 s4, s20, s33
	s_addc_u32 s5, s68, 0
	s_waitcnt vmcnt(7)
	v_cvt_f32_u32_e32 v16, v153
	v_cvt_f32_u32_e32 v17, v152
	s_andn2_b64 vcc, exec, s[38:39]
	v_fmac_f32_e32 v17, 0x4f800000, v16
	v_fmamk_f32 v16, v17, 0x30000000, v234
	v_rsq_f32_e32 v24, v16
	s_nop 0
	v_mul_f32_e32 v20, 0xbfb8aa3b, v24
	v_pk_mul_f32 v[18:19], v[14:15], v[20:21] op_sel_hi:[1,0]
	v_pk_mul_f32 v[16:17], v[12:13], v[20:21] op_sel_hi:[1,0]
	v_pk_mul_f32 v[22:23], v[6:7], v[20:21] op_sel_hi:[1,0]
	v_pk_mul_f32 v[20:21], v[4:5], v[20:21] op_sel_hi:[1,0]
	v_mul_f32_e32 v24, v24, v24
	v_pk_mul_f32 v[26:27], v[10:11], v[24:25] op_sel_hi:[1,0]
	v_exp_f32_e32 v16, v16
	v_exp_f32_e32 v20, v20
	v_exp_f32_e32 v17, v17
	v_exp_f32_e32 v21, v21
	v_exp_f32_e32 v18, v18
	v_exp_f32_e32 v22, v22
	v_exp_f32_e32 v19, v19
	v_exp_f32_e32 v23, v23
	v_pk_mul_f32 v[28:29], v[8:9], v[24:25] op_sel_hi:[1,0]
	v_pk_add_f32 v[8:9], v[16:17], 1.0 op_sel_hi:[1,0]
	v_pk_add_f32 v[10:11], v[18:19], 1.0 op_sel_hi:[1,0]
	v_pk_add_f32 v[14:15], v[22:23], 1.0 op_sel_hi:[1,0]
	v_pk_add_f32 v[12:13], v[20:21], 1.0 op_sel_hi:[1,0]
	v_pk_mul_f32 v[2:3], v[2:3], v[24:25] op_sel_hi:[1,0]
	v_pk_mul_f32 v[0:1], v[0:1], v[24:25] op_sel_hi:[1,0]
	v_rcp_f32_e32 v8, v8
	v_rcp_f32_e32 v12, v12
	v_rcp_f32_e32 v9, v9
	v_rcp_f32_e32 v13, v13
	v_rcp_f32_e32 v10, v10
	v_rcp_f32_e32 v14, v14
	v_rcp_f32_e32 v11, v11
	v_rcp_f32_e32 v15, v15
	s_nop 0
	v_pk_mul_f32 v[4:5], v[26:27], v[10:11]
	v_pk_mul_f32 v[6:7], v[28:29], v[8:9]
	v_pk_mul_f32 v[8:9], v[2:3], v[14:15]
	v_pk_mul_f32 v[2:3], v[0:1], v[12:13]
	v_cvt_pk_bf16_f32 v0, v6, v7
	v_cvt_pk_bf16_f32 v1, v4, v5
	v_cvt_pk_bf16_f32 v2, v2, v3
	v_cvt_pk_bf16_f32 v3, v8, v9
	v_lshl_add_u64 v[4:5], s[4:5], 0, v[82:83]
	s_mov_b64 s[4:5], -1
	global_store_dwordx4 v[4:5], v[0:3], off nt
	s_cbranch_vccnz .LBB0_791
	s_andn2_b64 vcc, exec, s[0:1]
	s_cbranch_vccnz .LBB0_790
	s_nop 0
	s_branch .LBB0_790

.LBB0_802:
	v_readfirstlane_b32 s100, v240
	v_readlane_b32 s98, v254, 19
	v_readlane_b32 s99, v254, 20
	v_readlane_b32 s32, v253, 45
	v_readlane_b32 vcc_lo, v253, 39
	s_lshr_b32 s100, s100, 7
	s_cmp_eq_u32 s100, 1
	s_cselect_b32 s32, vcc_lo, s32
	v_readlane_b32 vcc_lo, v253, 42
	s_cmp_eq_u32 s100, 2
	s_cselect_b32 s32, vcc_lo, s32
	v_readlane_b32 vcc_lo, v253, 46
	s_cmp_eq_u32 s100, 3
	s_cselect_b32 s32, vcc_lo, s32
	s_add_u32 s98, s98, 0x5a00000
	s_addc_u32 s99, s99, 0
	v_and_b32_e32 v96, 0x7f, v240
	v_lshlrev_b32_e32 v96, 7, v96
	v_add_u32_e32 v96, s32, v96
	v_mov_b32_e32 v97, 0
	v_lshl_add_u64 v[96:97], s[98:99], 0, v[96:97]
	global_load_dword v98, v[96:97], off
	v_readlane_b32 s0, v254, 18
	s_add_i32 s16, s0, 6
	s_cmp_ge_i32 s16, s91
	s_cbranch_scc1 .LBB0_871
	v_readlane_b32 s2, v250, 55
	v_readlane_b32 s3, v250, 56
	s_mov_b64 s[0:1], -1
	s_and_b64 vcc, exec, s[2:3]
	s_cbranch_vccz .LBB0_855
	s_waitcnt vmcnt(1)
	v_readlane_b32 s0, v251, 12
	v_readlane_b32 s1, v251, 13
	s_andn2_b64 vcc, exec, s[0:1]
	s_waitcnt lgkmcnt(0)
	s_barrier
	s_cbranch_vccnz .LBB0_854
	v_mov_b32_e32 v0, v81
	s_nop 0
	v_mbcnt_lo_u32_b32 v0, -1, v0
	v_mbcnt_hi_u32_b32 v0, -1, v0
	v_cmp_eq_u32_e32 vcc, 0, v0
	s_and_saveexec_b64 s[0:1], vcc
	s_cbranch_execz .LBB0_853
	v_readlane_b32 s2, v250, 5
	s_waitcnt vmcnt(0) expcnt(0) lgkmcnt(0)
	s_nop 0
	v_mov_b32_e32 v0, s2
	ds_read_b32 v2, v0
	ds_read_b32 v0, v0 offset:4
	s_waitcnt lgkmcnt(1)
	v_cmp_ne_u32_e32 vcc, 0, v2
	s_cbranch_vccnz .LBB0_821
	v_readlane_b32 s4, v250, 0
	v_readlane_b32 s5, v250, 1
	s_load_dwordx2 s[2:3], s[4:5], 0x4
	s_mov_b32 s9, 1
	s_waitcnt lgkmcnt(0)
	s_mul_i32 s8, s2, s33
	s_mul_i32 s8, s8, s3
	s_branch .LBB0_809

.LBB0_871:
	s_cmp_gt_i32 s90, s16
	s_cselect_b64 s[0:1], -1, 0
	s_cmp_ge_i32 s16, s91
	s_cselect_b64 s[2:3], -1, 0
	s_or_b64 s[0:1], s[0:1], s[2:3]
	s_and_b64 vcc, exec, s[0:1]
	s_cbranch_vccnz .LBB0_130
	v_mov_b32_e32 v0, v81
	s_and_b64 vcc, exec, s[80:81]
	v_mbcnt_lo_u32_b32 v0, -1, v0
	v_mbcnt_hi_u32_b32 v0, -1, v0
	v_add_u32_e32 v0, s69, v0
	s_nop 0
	v_readfirstlane_b32 s2, v0
	s_cbranch_vccnz .LBB0_908
	v_readlane_b32 s0, v254, 19
	v_readlane_b32 s1, v254, 20
	s_add_u32 s52, s0, 0x5a00000
	s_addc_u32 s0, s1, 0
	s_ashr_i32 s4, s2, 6
	s_lshl_b32 s5, s4, 10
	s_add_i32 s31, s5, 0x100
	s_waitcnt lgkmcnt(0)
	v_lshlrev_b32_e32 v220, 4, v0
	s_and_b32 s53, s0, 0xffff
	s_mov_b32 s55, s59
	s_add_i32 s51, s31, 0x10000
	v_readlane_b32 s0, v253, 45
	s_mov_b32 m0, s51
	s_nop 0
	buffer_load_dwordx4 v220, s[52:55], s0 offen lds
	v_add_u32_e32 v221, 0x2000, v220
	s_add_i32 s74, s31, 0x12000
	s_mov_b32 m0, s74
	s_nop 0
	buffer_load_dwordx4 v221, s[52:55], s0 offen lds
	s_add_i32 s75, s31, 0x14000
	v_readlane_b32 s0, v253, 39
	s_mov_b32 m0, s75
	s_nop 0
	buffer_load_dwordx4 v220, s[52:55], s0 offen lds
	s_add_i32 s76, s31, 0x16000
	s_mov_b32 m0, s76
	s_nop 0
	buffer_load_dwordx4 v221, s[52:55], s0 offen lds
	v_readlane_b32 s0, v253, 43
	s_mov_b32 m0, s31
	s_nop 0
	buffer_load_dwordx4 v220, s[20:23], s0 offen lds
	s_add_i32 s77, s31, 0x2000
	s_mov_b32 m0, s77
	s_nop 0
	buffer_load_dwordx4 v221, s[20:23], s0 offen lds
	s_add_i32 s78, s31, 0x4000
	v_readlane_b32 s6, v253, 41
	s_mov_b32 m0, s78
	s_nop 0
	buffer_load_dwordx4 v220, s[20:23], s6 offen lds
	s_ashr_i32 s3, s2, 8
	s_add_i32 s79, s31, 0x6000
	s_mov_b32 m0, s79
	s_nop 0
	buffer_load_dwordx4 v221, s[20:23], s6 offen lds
	v_readlane_b32 s32, v253, 42
	v_readlane_b32 s98, v253, 44
	v_readlane_b32 s99, v253, 46
	s_nop 2
	s_add_i32 m0, s31, 0x18000
	s_nop 0
	buffer_load_dwordx4 v220, s[52:55], s32 offen lds
	s_add_i32 m0, s31, 0x1a000
	s_nop 0
	buffer_load_dwordx4 v221, s[52:55], s32 offen lds
	s_add_i32 m0, s31, 0x8000
	s_nop 0
	buffer_load_dwordx4 v220, s[20:23], s98 offen lds
	s_add_i32 m0, s31, 0xa000
	s_nop 0
	buffer_load_dwordx4 v221, s[20:23], s98 offen lds
	s_add_i32 m0, s31, 0x1c000
	s_nop 0
	buffer_load_dwordx4 v220, s[52:55], s99 offen lds
	s_add_i32 m0, s31, 0x1e000
	s_nop 0
	buffer_load_dwordx4 v221, s[52:55], s99 offen lds
	s_cmp_eq_u32 s3, 1
	s_cselect_b64 s[0:1], -1, 0
	s_cmp_lg_u32 s3, 1
	s_cbranch_scc1 .LBB0_875
	s_nop 0

.Lpeel_p6:
	s_waitcnt lgkmcnt(0)
	v_add_u32_e32 v156, 0x10000, v222
	v_add_u32_e32 v180, 0x14000, v222
	ds_read_b128 v[128:131], v156
	ds_read_b128 v[140:143], v156 offset:1024
	ds_read_b128 v[152:155], v156 offset:2048
	ds_read_b128 v[156:159], v156 offset:3072
	ds_read_b128 v[168:171], v180
	ds_read_b128 v[172:175], v180 offset:1024
	ds_read_b128 v[176:179], v180 offset:2048
	ds_read_b128 v[180:183], v180 offset:3072
	s_add_i32 s11, s8, 0xffea4000
	s_cmpk_eq_i32 s10, 0x54
	s_cselect_b32 s13, s6, s11
	s_cselect_b32 s12, s7, s9
	s_or_b32 s11, s13, 0x4000
	ds_read_b128 v[184:187], v223
	ds_read_b128 v[188:191], v223 offset:1024
	ds_read_b128 v[192:195], v223 offset:2048
	ds_read_b128 v[196:199], v223 offset:3072
	ds_read_b128 v[200:203], v223 offset:4096
	ds_read_b128 v[204:207], v223 offset:5120
	ds_read_b128 v[224:227], v223 offset:6144
	ds_read_b128 v[228:231], v223 offset:7168
	s_mov_b32 m0, s87
	s_nop 0
	buffer_load_dwordx4 v220, s[20:23], s8 offen lds
	s_nop 0
	s_mov_b32 m0, s89
	s_nop 0
	buffer_load_dwordx4 v221, s[20:23], s8 offen lds
	s_waitcnt vmcnt(24)
	s_waitcnt lgkmcnt(0)
	s_cmp_lg_u32 s101, 0
	s_cbranch_scc1 .Lhbp_p6_0
	s_barrier

.Lhbp_p6_1:
	ds_read_b128 v[184:187], v223 offset:16384
	ds_read_b128 v[188:191], v223 offset:17408
	ds_read_b128 v[192:195], v223 offset:18432
	ds_read_b128 v[196:199], v223 offset:19456
	ds_read_b128 v[200:203], v223 offset:20480
	ds_read_b128 v[204:207], v223 offset:21504
	ds_read_b128 v[224:227], v223 offset:22528
	ds_read_b128 v[228:231], v223 offset:23552
	s_mov_b32 m0, s51
	s_nop 0
	buffer_load_dwordx4 v220, s[52:55], s12 offen lds
	s_add_i32 s14, s12, 0x160000
	s_mov_b32 m0, s74
	s_nop 0
	buffer_load_dwordx4 v221, s[52:55], s12 offen lds
	s_nop 0
	s_mov_b32 m0, s75
	s_nop 0
	buffer_load_dwordx4 v220, s[52:55], s14 offen lds
	s_nop 0
	s_mov_b32 m0, s76
	s_nop 0
	buffer_load_dwordx4 v221, s[52:55], s14 offen lds
	s_nop 0
	s_mov_b32 m0, s31
	s_nop 0
	buffer_load_dwordx4 v220, s[20:23], s13 offen lds
	s_nop 0
	s_mov_b32 m0, s77
	s_nop 0
	buffer_load_dwordx4 v221, s[20:23], s13 offen lds
	s_waitcnt vmcnt(24)
	s_waitcnt lgkmcnt(0)
	s_cmp_lg_u32 s101, 0
	s_cbranch_scc1 .Lhbp_p6_2
	s_barrier

.Lhbp_p6_3:
	v_add_u32_e32 v156, 0x18000, v222
	v_add_u32_e32 v180, 0x1c000, v222
	ds_read_b128 v[128:131], v156
	ds_read_b128 v[140:143], v156 offset:1024
	ds_read_b128 v[152:155], v156 offset:2048
	ds_read_b128 v[156:159], v156 offset:3072
	ds_read_b128 v[168:171], v180
	ds_read_b128 v[172:175], v180 offset:1024
	ds_read_b128 v[176:179], v180 offset:2048
	ds_read_b128 v[180:183], v180 offset:3072
	ds_read_b128 v[184:187], v223 offset:32768
	ds_read_b128 v[188:191], v223 offset:33792
	ds_read_b128 v[192:195], v223 offset:34816
	ds_read_b128 v[196:199], v223 offset:35840
	ds_read_b128 v[200:203], v223 offset:36864
	ds_read_b128 v[204:207], v223 offset:37888
	ds_read_b128 v[224:227], v223 offset:38912
	ds_read_b128 v[228:231], v223 offset:39936
	s_add_i32 s13, s13, 0x160000
	s_mov_b32 m0, s78
	s_nop 0
	buffer_load_dwordx4 v220, s[20:23], s13 offen lds
	s_nop 0
	s_mov_b32 m0, s79
	s_nop 0
	buffer_load_dwordx4 v221, s[20:23], s13 offen lds
	s_waitcnt vmcnt(8)
	s_waitcnt lgkmcnt(0)
	s_cmp_lg_u32 s101, 0
	s_cbranch_scc1 .Lhbp_p6_4
	s_barrier

.Lhbp_p6_5:
	ds_read_b128 v[184:187], v223 offset:49152
	ds_read_b128 v[188:191], v223 offset:50176
	ds_read_b128 v[192:195], v223 offset:51200
	ds_read_b128 v[196:199], v223 offset:52224
	ds_read_b128 v[200:203], v223 offset:53248
	ds_read_b128 v[204:207], v223 offset:54272
	ds_read_b128 v[224:227], v223 offset:55296
	ds_read_b128 v[228:231], v223 offset:56320
	s_or_b32 s13, s12, 0x4000
	s_mov_b32 m0, s34
	s_nop 0
	buffer_load_dwordx4 v220, s[52:55], s13 offen lds
	s_add_i32 s12, s12, 0x164000
	s_mov_b32 m0, s82
	s_nop 0
	buffer_load_dwordx4 v221, s[52:55], s13 offen lds
	s_nop 0
	s_mov_b32 m0, s85
	s_nop 0
	buffer_load_dwordx4 v220, s[52:55], s12 offen lds
	s_nop 0
	s_mov_b32 m0, s86
	s_nop 0
	buffer_load_dwordx4 v221, s[52:55], s12 offen lds
	s_nop 0
	s_mov_b32 m0, s83
	s_nop 0
	buffer_load_dwordx4 v220, s[20:23], s11 offen lds
	s_nop 0
	s_mov_b32 m0, s84
	s_nop 0
	buffer_load_dwordx4 v221, s[20:23], s11 offen lds
	s_waitcnt vmcnt(8)
	s_waitcnt lgkmcnt(0)
	s_cmp_lg_u32 s101, 0
	s_cbranch_scc1 .Lhbp_p6_6
	s_barrier

.LBB0_885:
	v_add_u32_e32 v156, 0x10000, v222
	v_add_u32_e32 v180, 0x14000, v222
	ds_read_b128 v[128:131], v156
	ds_read_b128 v[140:143], v156 offset:1024
	ds_read_b128 v[152:155], v156 offset:2048
	ds_read_b128 v[156:159], v156 offset:3072
	ds_read_b128 v[168:171], v180
	ds_read_b128 v[172:175], v180 offset:1024
	ds_read_b128 v[176:179], v180 offset:2048
	ds_read_b128 v[180:183], v180 offset:3072
	s_add_i32 s11, s8, 0xffea4000
	s_cmpk_eq_i32 s10, 0x54
	s_cselect_b32 s13, s6, s11
	s_cselect_b32 s12, s7, s9
	s_or_b32 s11, s13, 0x4000
	ds_read_b128 v[184:187], v223
	ds_read_b128 v[188:191], v223 offset:1024
	ds_read_b128 v[192:195], v223 offset:2048
	ds_read_b128 v[196:199], v223 offset:3072
	ds_read_b128 v[200:203], v223 offset:4096
	ds_read_b128 v[204:207], v223 offset:5120
	ds_read_b128 v[224:227], v223 offset:6144
	ds_read_b128 v[228:231], v223 offset:7168
	s_mov_b32 m0, s87
	s_nop 0
	buffer_load_dwordx4 v220, s[20:23], s8 offen lds
	s_nop 0
	s_mov_b32 m0, s89
	s_nop 0
	buffer_load_dwordx4 v221, s[20:23], s8 offen lds
	s_waitcnt vmcnt(8)
	s_waitcnt lgkmcnt(0)
	s_cmp_lg_u32 s101, 0
	s_cbranch_scc1 .Lhb_p6_0
	s_barrier

.Lhb_p6_1:
	ds_read_b128 v[184:187], v223 offset:16384
	ds_read_b128 v[188:191], v223 offset:17408
	ds_read_b128 v[192:195], v223 offset:18432
	ds_read_b128 v[196:199], v223 offset:19456
	ds_read_b128 v[200:203], v223 offset:20480
	ds_read_b128 v[204:207], v223 offset:21504
	ds_read_b128 v[224:227], v223 offset:22528
	ds_read_b128 v[228:231], v223 offset:23552
	s_mov_b32 m0, s51
	s_nop 0
	buffer_load_dwordx4 v220, s[52:55], s12 offen lds
	s_add_i32 s14, s12, 0x160000
	s_mov_b32 m0, s74
	s_nop 0
	buffer_load_dwordx4 v221, s[52:55], s12 offen lds
	s_nop 0
	s_mov_b32 m0, s75
	s_nop 0
	buffer_load_dwordx4 v220, s[52:55], s14 offen lds
	s_nop 0
	s_mov_b32 m0, s76
	s_nop 0
	buffer_load_dwordx4 v221, s[52:55], s14 offen lds
	s_nop 0
	s_mov_b32 m0, s31
	s_nop 0
	buffer_load_dwordx4 v220, s[20:23], s13 offen lds
	s_nop 0
	s_mov_b32 m0, s77
	s_nop 0
	buffer_load_dwordx4 v221, s[20:23], s13 offen lds
	s_waitcnt vmcnt(8)
	s_waitcnt lgkmcnt(0)
	s_cmp_lg_u32 s101, 0
	s_cbranch_scc1 .Lhb_p6_2
	s_barrier

.Lhb_p6_7:
	s_add_i32 s10, s10, 2
	s_add_i32 s8, s8, 0x8000
	s_add_i32 s9, s9, 0x8000
	s_cmpk_gt_u32 s10, 0x55
	s_cbranch_scc0 .LBB0_885
	s_and_b64 vcc, exec, s[2:3]
	s_cbranch_vccz .LBB0_888
	s_nop 0

.LBB0_904:
	s_or_b64 exec, exec, s[4:5]
	s_andn2_b64 vcc, exec, s[38:39]
	s_mov_b64 s[4:5], -1
	s_cbranch_vccnz .LBB0_877
	s_andn2_b64 vcc, exec, s[0:1]
	s_cbranch_vccnz .LBB0_876
	s_nop 0
	s_branch .LBB0_876
